# hipcc per-phase s_setprio flips removed from the five GEMM K-loops, no static raise
# speedup vs baseline: 1.0122x; 1.0122x over previous
; #define PG8_STAGE(bufoff, gbase, voff) do { _Pragma("unroll") for (int _i = 0; _i < 2; ++_i) \
;         __builtin_amdgcn_global_load_lds((const unsigned*)((const char*)(gbase) + (voff)[_i]), (PG8_LAS unsigned*)(lds + (bufoff) + ldsw + _i * 8192), 16, 0, 0); } while (0)
; #define PG8_LDA(dst, b, h) do { _Pragma("unroll") for (int m = 0; m < 4; ++m) _Pragma("unroll") for (int k = 0; k < 2; ++k) dst[m][k] = *(const PG8_LAS bf16x8*)(lds + PG8_SA(b, h) + aoff + m * 2048 + k * 1024); } while (0)
; #define PG8_LDB(dst, b, h) do { _Pragma("unroll") for (int n = 0; n < 2; ++n) _Pragma("unroll") for (int k = 0; k < 2; ++k) dst[n][k] = *(const PG8_LAS bf16x8*)(lds + PG8_SB(b, h) + boff + n * 2048 + k * 1024); } while (0)
; #define PG8_WAIT_V(n) asm volatile("s_waitcnt vmcnt(" #n ")" ::: "memory")
; #define PG8_WAIT_L(n) asm volatile("s_waitcnt lgkmcnt(" #n ")" ::: "memory")
; #define PG8_BAR __builtin_amdgcn_s_barrier()
; #define PG8_SCHED __builtin_amdgcn_sched_barrier(0)
; template <class Epi, class Sched, bool ALIGN_EPI = false, bool SP2 = false>
; __device__ __forceinline__ void gemm_phase(PG8_LAS unsigned char* lds, const Gemm g, const Sched& S, const Epi& E, const int tid) {
;     ...
;         const bool has_next = S.next(ui + 1, nxt);
;         const char* nA = has_next ? (const char*)g.A + (size_t)nxt.pm * tstep : cA; const char* nB = has_next ? (const char*)g.Bt + (size_t)nxt.pn * tstep : cB;
;         for (int t = 0; t < nt; t += 2) {
;             const bool last = (t == nt - 2);
;             const char* a1 = cA + (size_t)(t + 1) * kstep;
;             const char* a2 = last ? nA : cA + (size_t)(t + 2) * kstep; const char* b2 = last ? nB : cB + (size_t)(t + 2) * kstep;
;             const char* a3 = a2 + kstep; const char* b3 = b2 + kstep;
;             if (last && has_next) S.a_ready(nxt);
;             if constexpr (SP2) {
;             PG8_LDB(B0, 0, 0); PG8_LDB(B1, 0, 1); PG8_SCHED; PG8_LDA(At, 0, 0); PG8_STAGE(PG8_SA(1, 1), a1 + hstep, voffA);
;             PG8_WAIT_V(8); PG8_WAIT_L(0); PG8_BAR; PG8_MMA(0, 0, At, B0); PG8_MMA(0, 1, At, B1); PG8_BAR; PG8_SCHED;
;             PG8_LDA(At, 0, 1); PG8_STAGE(PG8_SB(0, 0), b2, voffB); PG8_STAGE(PG8_SB(0, 1), b2 + hstep, voffB); PG8_STAGE(PG8_SA(0, 0), a2, voffA);
;             PG8_WAIT_V(8); PG8_WAIT_L(0); PG8_BAR; PG8_MMA(1, 0, At, B0); PG8_MMA(1, 1, At, B1); PG8_BAR; PG8_SCHED;
.LBB0_99:
	s_add_u32 s20, s18, 0xfffc0080
	s_addc_u32 s21, s19, -1
	s_add_i32 s50, 0, 0x10000
	s_cmp_eq_u32 s49, 12
	s_cselect_b32 s23, s13, s21
	s_cselect_b32 s22, s45, s20
	s_cselect_b32 s21, s11, s48
	s_cselect_b32 s20, s46, s47
	s_add_i32 s52, 0, 0x14000
	v_add_u32_e32 v132, s50, v153
	v_add_u32_e32 v148, s52, v153
	ds_read_b128 v[116:119], v132
	ds_read_b128 v[120:123], v132 offset:1024
	ds_read_b128 v[124:127], v132 offset:2048
	ds_read_b128 v[132:135], v132 offset:3072
	ds_read_b128 v[178:181], v148
	ds_read_b128 v[182:185], v148 offset:1024
	ds_read_b128 v[186:189], v148 offset:2048
	ds_read_b128 v[190:193], v148 offset:3072
	v_lshl_add_u64 v[148:149], s[18:19], 0, v[172:173]
	s_add_i32 m0, s36, 0xc000
	ds_read_b128 v[194:197], v176
	ds_read_b128 v[198:201], v176 offset:1024
	ds_read_b128 v[202:205], v176 offset:2048
	ds_read_b128 v[206:209], v176 offset:3072
	ds_read_b128 v[210:213], v176 offset:4096
	ds_read_b128 v[214:217], v176 offset:5120
	ds_read_b128 v[218:221], v176 offset:6144
	ds_read_b128 v[222:225], v176 offset:7168
	global_load_lds_dwordx4 v[148:149], off
	v_lshl_add_u64 v[148:149], s[18:19], 0, v[174:175]
	s_add_i32 m0, s36, 0xe000
	s_nop 0
	global_load_lds_dwordx4 v[148:149], off
	s_waitcnt vmcnt(8)
	s_waitcnt lgkmcnt(0)
	s_barrier
	s_waitcnt lgkmcnt(0)
	v_mfma_f32_16x16x32_bf16 v[144:147], v[116:119], v[194:197], v[144:147]
	v_mfma_f32_16x16x32_bf16 v[140:143], v[124:127], v[194:197], v[140:143]
	v_mfma_f32_16x16x32_bf16 v[112:115], v[116:119], v[202:205], v[112:115]
	v_mfma_f32_16x16x32_bf16 v[108:111], v[124:127], v[202:205], v[108:111]
	v_mfma_f32_16x16x32_bf16 v[96:99], v[116:119], v[210:213], v[96:99]
	v_mfma_f32_16x16x32_bf16 v[92:95], v[124:127], v[210:213], v[92:95]
	v_mfma_f32_16x16x32_bf16 v[80:83], v[116:119], v[218:221], v[80:83]
	v_mfma_f32_16x16x32_bf16 v[76:79], v[124:127], v[218:221], v[76:79]
	v_mfma_f32_16x16x32_bf16 v[144:147], v[120:123], v[198:201], v[144:147]
	v_mfma_f32_16x16x32_bf16 v[140:143], v[132:135], v[198:201], v[140:143]
	v_mfma_f32_16x16x32_bf16 v[112:115], v[120:123], v[206:209], v[112:115]
	v_mfma_f32_16x16x32_bf16 v[108:111], v[132:135], v[206:209], v[108:111]
	v_mfma_f32_16x16x32_bf16 v[96:99], v[120:123], v[214:217], v[96:99]
	v_mfma_f32_16x16x32_bf16 v[92:95], v[132:135], v[214:217], v[92:95]
	v_mfma_f32_16x16x32_bf16 v[80:83], v[120:123], v[222:225], v[80:83]
	v_mfma_f32_16x16x32_bf16 v[76:79], v[132:135], v[222:225], v[76:79]
	v_mfma_f32_16x16x32_bf16 v[136:139], v[178:181], v[194:197], v[136:139]
	v_mfma_f32_16x16x32_bf16 v[128:131], v[186:189], v[194:197], v[128:131]
	v_mfma_f32_16x16x32_bf16 v[104:107], v[178:181], v[202:205], v[104:107]
	v_mfma_f32_16x16x32_bf16 v[100:103], v[186:189], v[202:205], v[100:103]
	v_mfma_f32_16x16x32_bf16 v[88:91], v[178:181], v[210:213], v[88:91]
	v_mfma_f32_16x16x32_bf16 v[84:87], v[186:189], v[210:213], v[84:87]
	v_mfma_f32_16x16x32_bf16 v[72:75], v[178:181], v[218:221], v[72:75]
	v_mfma_f32_16x16x32_bf16 v[68:71], v[186:189], v[218:221], v[68:71]
	v_mfma_f32_16x16x32_bf16 v[136:139], v[182:185], v[198:201], v[136:139]
	v_mfma_f32_16x16x32_bf16 v[128:131], v[190:193], v[198:201], v[128:131]
	v_mfma_f32_16x16x32_bf16 v[104:107], v[182:185], v[206:209], v[104:107]
	v_mfma_f32_16x16x32_bf16 v[100:103], v[190:193], v[206:209], v[100:103]
	v_mfma_f32_16x16x32_bf16 v[88:91], v[182:185], v[214:217], v[88:91]
	v_mfma_f32_16x16x32_bf16 v[84:87], v[190:193], v[214:217], v[84:87]
	v_mfma_f32_16x16x32_bf16 v[72:75], v[182:185], v[222:225], v[72:75]
	v_mfma_f32_16x16x32_bf16 v[68:71], v[190:193], v[222:225], v[68:71]
	s_barrier
	s_add_i32 s50, s50, s26
	v_lshl_add_u64 v[148:149], s[20:21], 0, v[168:169]
	s_mov_b32 m0, s50
	ds_read_b128 v[194:197], v176 offset:16384
	ds_read_b128 v[198:201], v176 offset:17408
	ds_read_b128 v[202:205], v176 offset:18432
	ds_read_b128 v[206:209], v176 offset:19456
	ds_read_b128 v[210:213], v176 offset:20480
	ds_read_b128 v[214:217], v176 offset:21504
	ds_read_b128 v[218:221], v176 offset:22528
	ds_read_b128 v[222:225], v176 offset:23552
	global_load_lds_dwordx4 v[148:149], off
	s_add_i32 m0, s50, 0x2000
	s_add_u32 s50, s20, 0x40000
	v_lshl_add_u64 v[150:151], s[20:21], 0, v[0:1]
	s_addc_u32 s51, s21, 0
	s_add_i32 s52, s52, s26
	global_load_lds_dwordx4 v[150:151], off
	v_lshl_add_u64 v[226:227], s[50:51], 0, v[168:169]
	s_mov_b32 m0, s52
	v_lshl_add_u64 v[238:239], s[22:23], 0, v[166:167]
	global_load_lds_dwordx4 v[226:227], off
	v_lshl_add_u64 v[226:227], s[50:51], 0, v[0:1]
	s_add_i32 m0, s52, 0x2000
	s_nop 0
	global_load_lds_dwordx4 v[226:227], off
	v_lshl_add_u64 v[226:227], s[22:23], 0, v[170:171]
	s_mov_b32 m0, s36
	s_nop 0
	global_load_lds_dwordx4 v[226:227], off
	s_mov_b32 m0, s37
	s_nop 0
	global_load_lds_dwordx4 v[238:239], off
	s_waitcnt vmcnt(8)
	s_waitcnt lgkmcnt(0)
	s_barrier
; #define PG8_STAGE(bufoff, gbase, voff) do { _Pragma("unroll") for (int _i = 0; _i < 2; ++_i) \
;         __builtin_amdgcn_global_load_lds((const unsigned*)((const char*)(gbase) + (voff)[_i]), (PG8_LAS unsigned*)(lds + (bufoff) + ldsw + _i * 8192), 16, 0, 0); } while (0)
; #define PG8_LDA(dst, b, h) do { _Pragma("unroll") for (int m = 0; m < 4; ++m) _Pragma("unroll") for (int k = 0; k < 2; ++k) dst[m][k] = *(const PG8_LAS bf16x8*)(lds + PG8_SA(b, h) + aoff + m * 2048 + k * 1024); } while (0)
; #define PG8_LDB(dst, b, h) do { _Pragma("unroll") for (int n = 0; n < 2; ++n) _Pragma("unroll") for (int k = 0; k < 2; ++k) dst[n][k] = *(const PG8_LAS bf16x8*)(lds + PG8_SB(b, h) + boff + n * 2048 + k * 1024); } while (0)
; #define PG8_MMA(ai, bj, At, Bt) do { __builtin_amdgcn_s_setprio(1); _Pragma("unroll") for (int m = 0; m < 4; ++m) _Pragma("unroll") for (int n = 0; n < 2; ++n) _Pragma("unroll") for (int k = 0; k < 2; ++k) \
;         acc[ai][bj][m][n] = __builtin_amdgcn_mfma_f32_16x16x32_bf16(Bt[n][k], At[m][k], acc[ai][bj][m][n], 0, 0, 0); __builtin_amdgcn_s_setprio(0); } while (0)
; #define PG8_WAIT_V(n) asm volatile("s_waitcnt vmcnt(" #n ")" ::: "memory")
; #define PG8_WAIT_L(n) asm volatile("s_waitcnt lgkmcnt(" #n ")" ::: "memory")
; #define PG8_BAR __builtin_amdgcn_s_barrier()
; #define PG8_SCHED __builtin_amdgcn_sched_barrier(0)
; template <class Epi, class Sched, bool ALIGN_EPI = false, bool SP2 = false>
; __device__ __forceinline__ void gemm_phase(PG8_LAS unsigned char* lds, const Gemm g, const Sched& S, const Epi& E, const int tid) {
;     ...
;             PG8_WAIT_V(8); PG8_WAIT_L(0); PG8_BAR; PG8_MMA(1, 0, At, B0); PG8_MMA(1, 1, At, B1); PG8_BAR; PG8_SCHED;
;             PG8_LDB(B0, 1, 0); PG8_LDB(B1, 1, 1); PG8_SCHED; PG8_LDA(At, 1, 0); PG8_STAGE(PG8_SA(0, 1), a2 + hstep, voffA);
;             PG8_WAIT_V(8); PG8_WAIT_L(0); PG8_BAR; PG8_MMA(0, 0, At, B0); PG8_MMA(0, 1, At, B1); PG8_BAR; PG8_SCHED;
;             PG8_LDA(At, 1, 1); PG8_STAGE(PG8_SB(1, 0), b3, voffB); PG8_STAGE(PG8_SB(1, 1), b3 + hstep, voffB); PG8_STAGE(PG8_SA(1, 0), a3, voffA);
	s_waitcnt lgkmcnt(0)
	v_mfma_f32_16x16x32_bf16 v[64:67], v[116:119], v[194:197], v[64:67]
	v_mfma_f32_16x16x32_bf16 v[60:63], v[124:127], v[194:197], v[60:63]
	v_mfma_f32_16x16x32_bf16 v[56:59], v[116:119], v[202:205], v[56:59]
	v_mfma_f32_16x16x32_bf16 v[48:51], v[124:127], v[202:205], v[48:51]
	v_mfma_f32_16x16x32_bf16 v[40:43], v[116:119], v[210:213], v[40:43]
	v_mfma_f32_16x16x32_bf16 v[32:35], v[124:127], v[210:213], v[32:35]
	v_mfma_f32_16x16x32_bf16 v[24:27], v[116:119], v[218:221], v[24:27]
	v_mfma_f32_16x16x32_bf16 v[16:19], v[124:127], v[218:221], v[16:19]
	v_mfma_f32_16x16x32_bf16 v[64:67], v[120:123], v[198:201], v[64:67]
	v_mfma_f32_16x16x32_bf16 v[60:63], v[132:135], v[198:201], v[60:63]
	v_mfma_f32_16x16x32_bf16 v[56:59], v[120:123], v[206:209], v[56:59]
	v_mfma_f32_16x16x32_bf16 v[48:51], v[132:135], v[206:209], v[48:51]
	v_mfma_f32_16x16x32_bf16 v[40:43], v[120:123], v[214:217], v[40:43]
	v_mfma_f32_16x16x32_bf16 v[32:35], v[132:135], v[214:217], v[32:35]
	v_mfma_f32_16x16x32_bf16 v[24:27], v[120:123], v[222:225], v[24:27]
	v_mfma_f32_16x16x32_bf16 v[16:19], v[132:135], v[222:225], v[16:19]
	v_mfma_f32_16x16x32_bf16 v[52:55], v[178:181], v[194:197], v[52:55]
	v_mfma_f32_16x16x32_bf16 v[44:47], v[186:189], v[194:197], v[44:47]
	v_mfma_f32_16x16x32_bf16 v[36:39], v[178:181], v[202:205], v[36:39]
	v_mfma_f32_16x16x32_bf16 v[28:31], v[186:189], v[202:205], v[28:31]
	v_mfma_f32_16x16x32_bf16 v[20:23], v[178:181], v[210:213], v[20:23]
	v_mfma_f32_16x16x32_bf16 v[12:15], v[186:189], v[210:213], v[12:15]
	v_mfma_f32_16x16x32_bf16 v[8:11], v[178:181], v[218:221], v[8:11]
	v_mfma_f32_16x16x32_bf16 v[4:7], v[186:189], v[218:221], v[4:7]
	v_mfma_f32_16x16x32_bf16 v[52:55], v[182:185], v[198:201], v[52:55]
	v_mfma_f32_16x16x32_bf16 v[44:47], v[190:193], v[198:201], v[44:47]
	v_mfma_f32_16x16x32_bf16 v[36:39], v[182:185], v[206:209], v[36:39]
	v_mfma_f32_16x16x32_bf16 v[28:31], v[190:193], v[206:209], v[28:31]
	v_mfma_f32_16x16x32_bf16 v[20:23], v[182:185], v[214:217], v[20:23]
	v_mfma_f32_16x16x32_bf16 v[12:15], v[190:193], v[214:217], v[12:15]
	v_mfma_f32_16x16x32_bf16 v[8:11], v[182:185], v[222:225], v[8:11]
	v_mfma_f32_16x16x32_bf16 v[4:7], v[190:193], v[222:225], v[4:7]
	s_barrier
	s_add_i32 s50, 0, 0x18000
	s_add_i32 s51, 0, 0x1c000
	v_add_u32_e32 v132, s50, v153
	v_add_u32_e32 v177, s51, v153
	ds_read_b128 v[116:119], v132
	ds_read_b128 v[120:123], v132 offset:1024
	ds_read_b128 v[124:127], v132 offset:2048
	ds_read_b128 v[132:135], v132 offset:3072
	ds_read_b128 v[178:181], v177
	ds_read_b128 v[182:185], v177 offset:1024
	ds_read_b128 v[186:189], v177 offset:2048
	ds_read_b128 v[190:193], v177 offset:3072
	s_add_u32 s22, s22, 0x40000
	s_addc_u32 s23, s23, 0
	s_mov_b32 m0, s38
	v_lshl_add_u64 v[240:241], s[22:23], 0, v[170:171]
	ds_read_b128 v[194:197], v176 offset:32768
	ds_read_b128 v[198:201], v176 offset:33792
	ds_read_b128 v[202:205], v176 offset:34816
	ds_read_b128 v[206:209], v176 offset:35840
	ds_read_b128 v[210:213], v176 offset:36864
	ds_read_b128 v[214:217], v176 offset:37888
	ds_read_b128 v[218:221], v176 offset:38912
	ds_read_b128 v[222:225], v176 offset:39936
	global_load_lds_dwordx4 v[240:241], off
	v_lshl_add_u64 v[240:241], s[22:23], 0, v[166:167]
	s_mov_b32 m0, s39
	s_nop 0
	global_load_lds_dwordx4 v[240:241], off
	s_waitcnt vmcnt(8)
	s_waitcnt lgkmcnt(0)
	s_barrier
	s_waitcnt lgkmcnt(0)
	v_mfma_f32_16x16x32_bf16 v[144:147], v[116:119], v[194:197], v[144:147]
	v_mfma_f32_16x16x32_bf16 v[140:143], v[124:127], v[194:197], v[140:143]
	v_mfma_f32_16x16x32_bf16 v[112:115], v[116:119], v[202:205], v[112:115]
	v_mfma_f32_16x16x32_bf16 v[108:111], v[124:127], v[202:205], v[108:111]
	v_mfma_f32_16x16x32_bf16 v[96:99], v[116:119], v[210:213], v[96:99]
	v_mfma_f32_16x16x32_bf16 v[92:95], v[124:127], v[210:213], v[92:95]
	v_mfma_f32_16x16x32_bf16 v[80:83], v[116:119], v[218:221], v[80:83]
	v_mfma_f32_16x16x32_bf16 v[76:79], v[124:127], v[218:221], v[76:79]
	v_mfma_f32_16x16x32_bf16 v[144:147], v[120:123], v[198:201], v[144:147]
	v_mfma_f32_16x16x32_bf16 v[140:143], v[132:135], v[198:201], v[140:143]
	v_mfma_f32_16x16x32_bf16 v[112:115], v[120:123], v[206:209], v[112:115]
	v_mfma_f32_16x16x32_bf16 v[108:111], v[132:135], v[206:209], v[108:111]
	v_mfma_f32_16x16x32_bf16 v[96:99], v[120:123], v[214:217], v[96:99]
	v_mfma_f32_16x16x32_bf16 v[92:95], v[132:135], v[214:217], v[92:95]
	v_mfma_f32_16x16x32_bf16 v[80:83], v[120:123], v[222:225], v[80:83]
	v_mfma_f32_16x16x32_bf16 v[76:79], v[132:135], v[222:225], v[76:79]
	v_mfma_f32_16x16x32_bf16 v[136:139], v[178:181], v[194:197], v[136:139]
	v_mfma_f32_16x16x32_bf16 v[128:131], v[186:189], v[194:197], v[128:131]
	v_mfma_f32_16x16x32_bf16 v[104:107], v[178:181], v[202:205], v[104:107]
	v_mfma_f32_16x16x32_bf16 v[100:103], v[186:189], v[202:205], v[100:103]
	v_mfma_f32_16x16x32_bf16 v[88:91], v[178:181], v[210:213], v[88:91]
	v_mfma_f32_16x16x32_bf16 v[84:87], v[186:189], v[210:213], v[84:87]
	v_mfma_f32_16x16x32_bf16 v[72:75], v[178:181], v[218:221], v[72:75]
	v_mfma_f32_16x16x32_bf16 v[68:71], v[186:189], v[218:221], v[68:71]
	v_mfma_f32_16x16x32_bf16 v[136:139], v[182:185], v[198:201], v[136:139]
	v_mfma_f32_16x16x32_bf16 v[128:131], v[190:193], v[198:201], v[128:131]
	v_mfma_f32_16x16x32_bf16 v[104:107], v[182:185], v[206:209], v[104:107]
	v_mfma_f32_16x16x32_bf16 v[100:103], v[190:193], v[206:209], v[100:103]
	v_mfma_f32_16x16x32_bf16 v[88:91], v[182:185], v[214:217], v[88:91]
	v_mfma_f32_16x16x32_bf16 v[84:87], v[190:193], v[214:217], v[84:87]
	v_mfma_f32_16x16x32_bf16 v[72:75], v[182:185], v[222:225], v[72:75]
	v_mfma_f32_16x16x32_bf16 v[68:71], v[190:193], v[222:225], v[68:71]
	s_barrier
; #define PG8_STAGE(bufoff, gbase, voff) do { _Pragma("unroll") for (int _i = 0; _i < 2; ++_i) \
;         __builtin_amdgcn_global_load_lds((const unsigned*)((const char*)(gbase) + (voff)[_i]), (PG8_LAS unsigned*)(lds + (bufoff) + ldsw + _i * 8192), 16, 0, 0); } while (0)
; #define PG8_LDA(dst, b, h) do { _Pragma("unroll") for (int m = 0; m < 4; ++m) _Pragma("unroll") for (int k = 0; k < 2; ++k) dst[m][k] = *(const PG8_LAS bf16x8*)(lds + PG8_SA(b, h) + aoff + m * 2048 + k * 1024); } while (0)
; #define PG8_MMA(ai, bj, At, Bt) do { __builtin_amdgcn_s_setprio(1); _Pragma("unroll") for (int m = 0; m < 4; ++m) _Pragma("unroll") for (int n = 0; n < 2; ++n) _Pragma("unroll") for (int k = 0; k < 2; ++k) \
;         acc[ai][bj][m][n] = __builtin_amdgcn_mfma_f32_16x16x32_bf16(Bt[n][k], At[m][k], acc[ai][bj][m][n], 0, 0, 0); __builtin_amdgcn_s_setprio(0); } while (0)
; #define PG8_WAIT_V(n) asm volatile("s_waitcnt vmcnt(" #n ")" ::: "memory")
; #define PG8_WAIT_L(n) asm volatile("s_waitcnt lgkmcnt(" #n ")" ::: "memory")
; #define PG8_BAR __builtin_amdgcn_s_barrier()
; #define PG8_SCHED __builtin_amdgcn_sched_barrier(0)
; template <class Epi, class Sched, bool ALIGN_EPI = false, bool SP2 = false>
; __device__ __forceinline__ void gemm_phase(PG8_LAS unsigned char* lds, const Gemm g, const Sched& S, const Epi& E, const int tid) {
;     ...
;             PG8_WAIT_V(8); PG8_WAIT_L(0); PG8_BAR; PG8_MMA(0, 0, At, B0); PG8_MMA(0, 1, At, B1); PG8_BAR; PG8_SCHED;
;             PG8_LDA(At, 1, 1); PG8_STAGE(PG8_SB(1, 0), b3, voffB); PG8_STAGE(PG8_SB(1, 1), b3 + hstep, voffB); PG8_STAGE(PG8_SA(1, 0), a3, voffA);
;             PG8_WAIT_V(8); PG8_WAIT_L(0); PG8_BAR; PG8_MMA(1, 0, At, B0); PG8_MMA(1, 1, At, B1); PG8_BAR; PG8_SCHED;
	s_add_i32 s22, s50, s26
	v_lshl_add_u64 v[148:149], v[148:149], 0, s[0:1]
	s_mov_b32 m0, s22
	ds_read_b128 v[194:197], v176 offset:49152
	ds_read_b128 v[198:201], v176 offset:50176
	ds_read_b128 v[202:205], v176 offset:51200
	ds_read_b128 v[206:209], v176 offset:52224
	ds_read_b128 v[210:213], v176 offset:53248
	ds_read_b128 v[214:217], v176 offset:54272
	ds_read_b128 v[218:221], v176 offset:55296
	ds_read_b128 v[222:225], v176 offset:56320
	global_load_lds_dwordx4 v[148:149], off
	s_add_i32 m0, s22, 0x2000
	s_add_u32 s20, s20, 0x40080
	v_lshl_add_u64 v[148:149], v[150:151], 0, s[0:1]
	s_addc_u32 s21, s21, 0
	s_add_i32 s22, s51, s26
	global_load_lds_dwordx4 v[148:149], off
	v_lshl_add_u64 v[148:149], s[20:21], 0, v[168:169]
	s_mov_b32 m0, s22
	s_nop 0
	global_load_lds_dwordx4 v[148:149], off
	v_lshl_add_u64 v[148:149], s[20:21], 0, v[0:1]
	s_add_i32 m0, s22, 0x2000
	s_nop 0
	global_load_lds_dwordx4 v[148:149], off
	v_lshl_add_u64 v[148:149], v[226:227], 0, s[0:1]
	s_mov_b32 m0, s40
	s_nop 0
	global_load_lds_dwordx4 v[148:149], off
	v_lshl_add_u64 v[148:149], v[238:239], 0, s[0:1]
	s_mov_b32 m0, s41
	s_nop 0
	global_load_lds_dwordx4 v[148:149], off
	s_waitcnt vmcnt(8)
	s_waitcnt lgkmcnt(0)
	s_barrier
	s_waitcnt lgkmcnt(0)
	v_mfma_f32_16x16x32_bf16 v[64:67], v[116:119], v[194:197], v[64:67]
	v_mfma_f32_16x16x32_bf16 v[60:63], v[124:127], v[194:197], v[60:63]
	v_mfma_f32_16x16x32_bf16 v[56:59], v[116:119], v[202:205], v[56:59]
	v_mfma_f32_16x16x32_bf16 v[48:51], v[124:127], v[202:205], v[48:51]
	v_mfma_f32_16x16x32_bf16 v[40:43], v[116:119], v[210:213], v[40:43]
	v_mfma_f32_16x16x32_bf16 v[32:35], v[124:127], v[210:213], v[32:35]
	v_mfma_f32_16x16x32_bf16 v[24:27], v[116:119], v[218:221], v[24:27]
	v_mfma_f32_16x16x32_bf16 v[16:19], v[124:127], v[218:221], v[16:19]
	v_mfma_f32_16x16x32_bf16 v[64:67], v[120:123], v[198:201], v[64:67]
	v_mfma_f32_16x16x32_bf16 v[60:63], v[132:135], v[198:201], v[60:63]
	v_mfma_f32_16x16x32_bf16 v[56:59], v[120:123], v[206:209], v[56:59]
	v_mfma_f32_16x16x32_bf16 v[48:51], v[132:135], v[206:209], v[48:51]
	v_mfma_f32_16x16x32_bf16 v[40:43], v[120:123], v[214:217], v[40:43]
	v_mfma_f32_16x16x32_bf16 v[32:35], v[132:135], v[214:217], v[32:35]
	v_mfma_f32_16x16x32_bf16 v[24:27], v[120:123], v[222:225], v[24:27]
	v_mfma_f32_16x16x32_bf16 v[16:19], v[132:135], v[222:225], v[16:19]
	v_mfma_f32_16x16x32_bf16 v[52:55], v[178:181], v[194:197], v[52:55]
	v_mfma_f32_16x16x32_bf16 v[44:47], v[186:189], v[194:197], v[44:47]
	v_mfma_f32_16x16x32_bf16 v[36:39], v[178:181], v[202:205], v[36:39]
	v_mfma_f32_16x16x32_bf16 v[28:31], v[186:189], v[202:205], v[28:31]
	v_mfma_f32_16x16x32_bf16 v[20:23], v[178:181], v[210:213], v[20:23]
	v_mfma_f32_16x16x32_bf16 v[12:15], v[186:189], v[210:213], v[12:15]
	v_mfma_f32_16x16x32_bf16 v[8:11], v[178:181], v[218:221], v[8:11]
	v_mfma_f32_16x16x32_bf16 v[4:7], v[186:189], v[218:221], v[4:7]
	v_mfma_f32_16x16x32_bf16 v[52:55], v[182:185], v[198:201], v[52:55]
	v_mfma_f32_16x16x32_bf16 v[44:47], v[190:193], v[198:201], v[44:47]
	v_mfma_f32_16x16x32_bf16 v[36:39], v[182:185], v[206:209], v[36:39]
	v_mfma_f32_16x16x32_bf16 v[28:31], v[190:193], v[206:209], v[28:31]
	v_mfma_f32_16x16x32_bf16 v[20:23], v[182:185], v[214:217], v[20:23]
	v_mfma_f32_16x16x32_bf16 v[12:15], v[190:193], v[214:217], v[12:15]
	v_mfma_f32_16x16x32_bf16 v[8:11], v[182:185], v[222:225], v[8:11]
	v_mfma_f32_16x16x32_bf16 v[4:7], v[190:193], v[222:225], v[4:7]
	s_barrier
	s_add_i32 s49, s49, 2
	s_add_u32 s18, s18, 0x100
	s_addc_u32 s19, s19, 0
	s_add_u32 s47, s47, 0x100
	s_addc_u32 s48, s48, 0
	s_cmp_gt_u32 s49, 13
	s_cbranch_scc0 .LBB0_99
	s_and_b64 vcc, exec, s[8:9]
	s_cbranch_vccz .LBB0_102
	s_barrier

; #define PG8_STAGE(bufoff, gbase, voff) do { _Pragma("unroll") for (int _i = 0; _i < 2; ++_i) \
;         __builtin_amdgcn_global_load_lds((const unsigned*)((const char*)(gbase) + (voff)[_i]), (PG8_LAS unsigned*)(lds + (bufoff) + ldsw + _i * 8192), 16, 0, 0); } while (0)
; #define PG8_LDA(dst, b, h) do { _Pragma("unroll") for (int m = 0; m < 4; ++m) _Pragma("unroll") for (int k = 0; k < 2; ++k) dst[m][k] = *(const PG8_LAS bf16x8*)(lds + PG8_SA(b, h) + aoff + m * 2048 + k * 1024); } while (0)
; #define PG8_LDB(dst, b, h) do { _Pragma("unroll") for (int n = 0; n < 2; ++n) _Pragma("unroll") for (int k = 0; k < 2; ++k) dst[n][k] = *(const PG8_LAS bf16x8*)(lds + PG8_SB(b, h) + boff + n * 2048 + k * 1024); } while (0)
; #define PG8_WAIT_V(n) asm volatile("s_waitcnt vmcnt(" #n ")" ::: "memory")
; #define PG8_WAIT_L(n) asm volatile("s_waitcnt lgkmcnt(" #n ")" ::: "memory")
; #define PG8_BAR __builtin_amdgcn_s_barrier()
; #define PG8_SCHED __builtin_amdgcn_sched_barrier(0)
; template <class Epi, class Sched, bool ALIGN_EPI = false, bool SP2 = false>
; __device__ __forceinline__ void gemm_phase(PG8_LAS unsigned char* lds, const Gemm g, const Sched& S, const Epi& E, const int tid) {
;     ...
;         const bool has_next = S.next(ui + 1, nxt);
;         const char* nA = has_next ? (const char*)g.A + (size_t)nxt.pm * tstep : cA; const char* nB = has_next ? (const char*)g.Bt + (size_t)nxt.pn * tstep : cB;
;         for (int t = 0; t < nt; t += 2) {
;             const bool last = (t == nt - 2);
;             const char* a1 = cA + (size_t)(t + 1) * kstep;
;             const char* a2 = last ? nA : cA + (size_t)(t + 2) * kstep; const char* b2 = last ? nB : cB + (size_t)(t + 2) * kstep;
;             const char* a3 = a2 + kstep; const char* b3 = b2 + kstep;
;             if (last && has_next) S.a_ready(nxt);
;             if constexpr (SP2) {
;             PG8_LDB(B0, 0, 0); PG8_LDB(B1, 0, 1); PG8_SCHED; PG8_LDA(At, 0, 0); PG8_STAGE(PG8_SA(1, 1), a1 + hstep, voffA);
;             PG8_WAIT_V(8); PG8_WAIT_L(0); PG8_BAR; PG8_MMA(0, 0, At, B0); PG8_MMA(0, 1, At, B1); PG8_BAR; PG8_SCHED;
;             PG8_LDA(At, 0, 1); PG8_STAGE(PG8_SB(0, 0), b2, voffB); PG8_STAGE(PG8_SB(0, 1), b2 + hstep, voffB); PG8_STAGE(PG8_SA(0, 0), a2, voffA);
;             PG8_WAIT_V(8); PG8_WAIT_L(0); PG8_BAR; PG8_MMA(1, 0, At, B0); PG8_MMA(1, 1, At, B1); PG8_BAR; PG8_SCHED;
.LBB0_293:
	s_add_u32 s26, s2, 0xfffc0080
	s_addc_u32 s27, s3, -1
	s_add_i32 s55, 0, 0x10000
	s_cmp_eq_u32 s54, 12
	s_cselect_b32 s37, s17, s27
	s_cselect_b32 s36, s23, s26
	v_add_u32_e32 v146, s55, v165
	s_cselect_b32 s27, s15, s53
	s_cselect_b32 s26, s51, s52
	s_add_i32 s58, 0, 0x14000
	ds_read_b128 v[166:169], v146
	ds_read_b128 v[172:175], v146 offset:1024
	ds_read_b128 v[176:179], v146 offset:2048
	ds_read_b128 v[180:183], v146 offset:3072
	v_add_u32_e32 v146, s58, v165
	ds_read_b128 v[184:187], v146
	ds_read_b128 v[188:191], v146 offset:1024
	ds_read_b128 v[192:195], v146 offset:2048
	ds_read_b128 v[196:199], v146 offset:3072
	v_lshl_add_u64 v[146:147], s[2:3], 0, v[142:143]
	s_add_i32 m0, s25, 0xc000
	ds_read_b128 v[200:203], v171
	ds_read_b128 v[204:207], v171 offset:1024
	ds_read_b128 v[208:211], v171 offset:2048
	ds_read_b128 v[212:215], v171 offset:3072
	ds_read_b128 v[216:219], v171 offset:4096
	ds_read_b128 v[220:223], v171 offset:5120
	ds_read_b128 v[224:227], v171 offset:6144
	ds_read_b128 v[238:241], v171 offset:7168
	global_load_lds_dwordx4 v[146:147], off
	v_lshl_add_u64 v[146:147], s[2:3], 0, v[144:145]
	s_add_i32 m0, s25, 0xe000
	s_nop 0
	global_load_lds_dwordx4 v[146:147], off
	s_waitcnt vmcnt(8)
	s_waitcnt lgkmcnt(0)
	s_barrier
	s_waitcnt lgkmcnt(0)
	v_mfma_f32_16x16x32_bf16 v[72:75], v[166:169], v[200:203], v[72:75]
	v_mfma_f32_16x16x32_bf16 v[68:71], v[176:179], v[200:203], v[68:71]
	v_mfma_f32_16x16x32_bf16 v[64:67], v[166:169], v[208:211], v[64:67]
	v_mfma_f32_16x16x32_bf16 v[60:63], v[176:179], v[208:211], v[60:63]
	v_mfma_f32_16x16x32_bf16 v[56:59], v[166:169], v[216:219], v[56:59]
	v_mfma_f32_16x16x32_bf16 v[52:55], v[176:179], v[216:219], v[52:55]
	v_mfma_f32_16x16x32_bf16 v[48:51], v[166:169], v[224:227], v[48:51]
	v_mfma_f32_16x16x32_bf16 v[44:47], v[176:179], v[224:227], v[44:47]
	v_mfma_f32_16x16x32_bf16 v[72:75], v[172:175], v[204:207], v[72:75]
	v_mfma_f32_16x16x32_bf16 v[68:71], v[180:183], v[204:207], v[68:71]
	v_mfma_f32_16x16x32_bf16 v[64:67], v[172:175], v[212:215], v[64:67]
	v_mfma_f32_16x16x32_bf16 v[60:63], v[180:183], v[212:215], v[60:63]
	v_mfma_f32_16x16x32_bf16 v[56:59], v[172:175], v[220:223], v[56:59]
	v_mfma_f32_16x16x32_bf16 v[52:55], v[180:183], v[220:223], v[52:55]
	v_mfma_f32_16x16x32_bf16 v[48:51], v[172:175], v[238:241], v[48:51]
	v_mfma_f32_16x16x32_bf16 v[44:47], v[180:183], v[238:241], v[44:47]
	v_mfma_f32_16x16x32_bf16 v[128:131], v[184:187], v[200:203], v[128:131]
	v_mfma_f32_16x16x32_bf16 v[124:127], v[192:195], v[200:203], v[124:127]
	v_mfma_f32_16x16x32_bf16 v[120:123], v[184:187], v[208:211], v[120:123]
	v_mfma_f32_16x16x32_bf16 v[116:119], v[192:195], v[208:211], v[116:119]
	v_mfma_f32_16x16x32_bf16 v[112:115], v[184:187], v[216:219], v[112:115]
	v_mfma_f32_16x16x32_bf16 v[108:111], v[192:195], v[216:219], v[108:111]
	v_mfma_f32_16x16x32_bf16 v[104:107], v[184:187], v[224:227], v[104:107]
	v_mfma_f32_16x16x32_bf16 v[100:103], v[192:195], v[224:227], v[100:103]
	v_mfma_f32_16x16x32_bf16 v[128:131], v[188:191], v[204:207], v[128:131]
	v_mfma_f32_16x16x32_bf16 v[124:127], v[196:199], v[204:207], v[124:127]
	v_mfma_f32_16x16x32_bf16 v[120:123], v[188:191], v[212:215], v[120:123]
	v_mfma_f32_16x16x32_bf16 v[116:119], v[196:199], v[212:215], v[116:119]
	v_mfma_f32_16x16x32_bf16 v[112:115], v[188:191], v[220:223], v[112:115]
	v_mfma_f32_16x16x32_bf16 v[108:111], v[196:199], v[220:223], v[108:111]
	v_mfma_f32_16x16x32_bf16 v[104:107], v[188:191], v[238:241], v[104:107]
	v_mfma_f32_16x16x32_bf16 v[100:103], v[196:199], v[238:241], v[100:103]
	s_barrier
	s_add_i32 s55, s55, s43
	v_lshl_add_u64 v[146:147], s[26:27], 0, v[132:133]
	s_mov_b32 m0, s55
	ds_read_b128 v[200:203], v171 offset:16384
	ds_read_b128 v[204:207], v171 offset:17408
	ds_read_b128 v[208:211], v171 offset:18432
	ds_read_b128 v[212:215], v171 offset:19456
	ds_read_b128 v[216:219], v171 offset:20480
	ds_read_b128 v[220:223], v171 offset:21504
	ds_read_b128 v[224:227], v171 offset:22528
	ds_read_b128 v[238:241], v171 offset:23552
	global_load_lds_dwordx4 v[146:147], off
	s_add_i32 m0, s55, 0x2000
	s_add_u32 s56, s26, 0x40000
	v_lshl_add_u64 v[148:149], s[26:27], 0, v[136:137]
	s_addc_u32 s57, s27, 0
	s_add_i32 s55, s58, s43
	global_load_lds_dwordx4 v[148:149], off
	v_lshl_add_u64 v[150:151], s[56:57], 0, v[132:133]
	s_mov_b32 m0, s55
	v_lshl_add_u64 v[242:243], s[36:37], 0, v[134:135]
	global_load_lds_dwordx4 v[150:151], off
	v_lshl_add_u64 v[150:151], s[56:57], 0, v[136:137]
	s_add_i32 m0, s55, 0x2000
	s_nop 0
	global_load_lds_dwordx4 v[150:151], off
	v_lshl_add_u64 v[150:151], s[36:37], 0, v[0:1]
	s_mov_b32 m0, s25
	s_nop 0
	global_load_lds_dwordx4 v[150:151], off
	s_mov_b32 m0, s44
	s_nop 0
	global_load_lds_dwordx4 v[242:243], off
	s_waitcnt vmcnt(8)
	s_waitcnt lgkmcnt(0)
	s_barrier
; #define PG8_STAGE(bufoff, gbase, voff) do { _Pragma("unroll") for (int _i = 0; _i < 2; ++_i) \
;         __builtin_amdgcn_global_load_lds((const unsigned*)((const char*)(gbase) + (voff)[_i]), (PG8_LAS unsigned*)(lds + (bufoff) + ldsw + _i * 8192), 16, 0, 0); } while (0)
; #define PG8_LDA(dst, b, h) do { _Pragma("unroll") for (int m = 0; m < 4; ++m) _Pragma("unroll") for (int k = 0; k < 2; ++k) dst[m][k] = *(const PG8_LAS bf16x8*)(lds + PG8_SA(b, h) + aoff + m * 2048 + k * 1024); } while (0)
; #define PG8_LDB(dst, b, h) do { _Pragma("unroll") for (int n = 0; n < 2; ++n) _Pragma("unroll") for (int k = 0; k < 2; ++k) dst[n][k] = *(const PG8_LAS bf16x8*)(lds + PG8_SB(b, h) + boff + n * 2048 + k * 1024); } while (0)
; #define PG8_MMA(ai, bj, At, Bt) do { __builtin_amdgcn_s_setprio(1); _Pragma("unroll") for (int m = 0; m < 4; ++m) _Pragma("unroll") for (int n = 0; n < 2; ++n) _Pragma("unroll") for (int k = 0; k < 2; ++k) \
;         acc[ai][bj][m][n] = __builtin_amdgcn_mfma_f32_16x16x32_bf16(Bt[n][k], At[m][k], acc[ai][bj][m][n], 0, 0, 0); __builtin_amdgcn_s_setprio(0); } while (0)
; #define PG8_WAIT_V(n) asm volatile("s_waitcnt vmcnt(" #n ")" ::: "memory")
; #define PG8_WAIT_L(n) asm volatile("s_waitcnt lgkmcnt(" #n ")" ::: "memory")
; #define PG8_BAR __builtin_amdgcn_s_barrier()
; #define PG8_SCHED __builtin_amdgcn_sched_barrier(0)
; template <class Epi, class Sched, bool ALIGN_EPI = false, bool SP2 = false>
; __device__ __forceinline__ void gemm_phase(PG8_LAS unsigned char* lds, const Gemm g, const Sched& S, const Epi& E, const int tid) {
;     ...
;             PG8_WAIT_V(8); PG8_WAIT_L(0); PG8_BAR; PG8_MMA(1, 0, At, B0); PG8_MMA(1, 1, At, B1); PG8_BAR; PG8_SCHED;
;             PG8_LDB(B0, 1, 0); PG8_LDB(B1, 1, 1); PG8_SCHED; PG8_LDA(At, 1, 0); PG8_STAGE(PG8_SA(0, 1), a2 + hstep, voffA);
;             PG8_WAIT_V(8); PG8_WAIT_L(0); PG8_BAR; PG8_MMA(0, 0, At, B0); PG8_MMA(0, 1, At, B1); PG8_BAR; PG8_SCHED;
;             PG8_LDA(At, 1, 1); PG8_STAGE(PG8_SB(1, 0), b3, voffB); PG8_STAGE(PG8_SB(1, 1), b3 + hstep, voffB); PG8_STAGE(PG8_SA(1, 0), a3, voffA);
	s_waitcnt lgkmcnt(0)
	v_mfma_f32_16x16x32_bf16 v[40:43], v[166:169], v[200:203], v[40:43]
	v_mfma_f32_16x16x32_bf16 v[36:39], v[176:179], v[200:203], v[36:39]
	v_mfma_f32_16x16x32_bf16 v[32:35], v[166:169], v[208:211], v[32:35]
	v_mfma_f32_16x16x32_bf16 v[28:31], v[176:179], v[208:211], v[28:31]
	v_mfma_f32_16x16x32_bf16 v[24:27], v[166:169], v[216:219], v[24:27]
	v_mfma_f32_16x16x32_bf16 v[20:23], v[176:179], v[216:219], v[20:23]
	v_mfma_f32_16x16x32_bf16 v[8:11], v[166:169], v[224:227], v[8:11]
	v_mfma_f32_16x16x32_bf16 v[4:7], v[176:179], v[224:227], v[4:7]
	v_mfma_f32_16x16x32_bf16 v[40:43], v[172:175], v[204:207], v[40:43]
	v_mfma_f32_16x16x32_bf16 v[36:39], v[180:183], v[204:207], v[36:39]
	v_mfma_f32_16x16x32_bf16 v[32:35], v[172:175], v[212:215], v[32:35]
	v_mfma_f32_16x16x32_bf16 v[28:31], v[180:183], v[212:215], v[28:31]
	v_mfma_f32_16x16x32_bf16 v[24:27], v[172:175], v[220:223], v[24:27]
	v_mfma_f32_16x16x32_bf16 v[20:23], v[180:183], v[220:223], v[20:23]
	v_mfma_f32_16x16x32_bf16 v[8:11], v[172:175], v[238:241], v[8:11]
	v_mfma_f32_16x16x32_bf16 v[4:7], v[180:183], v[238:241], v[4:7]
	v_mfma_f32_16x16x32_bf16 v[96:99], v[184:187], v[200:203], v[96:99]
	v_mfma_f32_16x16x32_bf16 v[92:95], v[192:195], v[200:203], v[92:95]
	v_mfma_f32_16x16x32_bf16 v[88:91], v[184:187], v[208:211], v[88:91]
	v_mfma_f32_16x16x32_bf16 v[84:87], v[192:195], v[208:211], v[84:87]
	v_mfma_f32_16x16x32_bf16 v[80:83], v[184:187], v[216:219], v[80:83]
	v_mfma_f32_16x16x32_bf16 v[76:79], v[192:195], v[216:219], v[76:79]
	v_mfma_f32_16x16x32_bf16 v[16:19], v[184:187], v[224:227], v[16:19]
	v_mfma_f32_16x16x32_bf16 v[12:15], v[192:195], v[224:227], v[12:15]
	v_mfma_f32_16x16x32_bf16 v[96:99], v[188:191], v[204:207], v[96:99]
	v_mfma_f32_16x16x32_bf16 v[92:95], v[196:199], v[204:207], v[92:95]
	v_mfma_f32_16x16x32_bf16 v[88:91], v[188:191], v[212:215], v[88:91]
	v_mfma_f32_16x16x32_bf16 v[84:87], v[196:199], v[212:215], v[84:87]
	v_mfma_f32_16x16x32_bf16 v[80:83], v[188:191], v[220:223], v[80:83]
	v_mfma_f32_16x16x32_bf16 v[76:79], v[196:199], v[220:223], v[76:79]
	v_mfma_f32_16x16x32_bf16 v[16:19], v[188:191], v[238:241], v[16:19]
	v_mfma_f32_16x16x32_bf16 v[12:15], v[196:199], v[238:241], v[12:15]
	s_barrier
	s_add_i32 s55, 0, 0x18000
	v_add_u32_e32 v153, s55, v165
	s_add_i32 s56, 0, 0x1c000
	ds_read_b128 v[166:169], v153
	ds_read_b128 v[172:175], v153 offset:1024
	ds_read_b128 v[176:179], v153 offset:2048
	ds_read_b128 v[180:183], v153 offset:3072
	v_add_u32_e32 v153, s56, v165
	ds_read_b128 v[184:187], v153
	ds_read_b128 v[188:191], v153 offset:1024
	ds_read_b128 v[192:195], v153 offset:2048
	ds_read_b128 v[196:199], v153 offset:3072
	s_add_u32 s36, s36, 0x40000
	s_addc_u32 s37, s37, 0
	s_mov_b32 m0, s45
	v_lshl_add_u64 v[244:245], s[36:37], 0, v[0:1]
	ds_read_b128 v[200:203], v171 offset:32768
	ds_read_b128 v[204:207], v171 offset:33792
	ds_read_b128 v[208:211], v171 offset:34816
	ds_read_b128 v[212:215], v171 offset:35840
	ds_read_b128 v[216:219], v171 offset:36864
	ds_read_b128 v[220:223], v171 offset:37888
	ds_read_b128 v[224:227], v171 offset:38912
	ds_read_b128 v[238:241], v171 offset:39936
	global_load_lds_dwordx4 v[244:245], off
	v_lshl_add_u64 v[244:245], s[36:37], 0, v[134:135]
	s_mov_b32 m0, s46
	s_nop 0
	global_load_lds_dwordx4 v[244:245], off
	s_waitcnt vmcnt(8)
	s_waitcnt lgkmcnt(0)
	s_barrier
	s_waitcnt lgkmcnt(0)
	v_mfma_f32_16x16x32_bf16 v[72:75], v[166:169], v[200:203], v[72:75]
	v_mfma_f32_16x16x32_bf16 v[68:71], v[176:179], v[200:203], v[68:71]
	v_mfma_f32_16x16x32_bf16 v[64:67], v[166:169], v[208:211], v[64:67]
	v_mfma_f32_16x16x32_bf16 v[60:63], v[176:179], v[208:211], v[60:63]
	v_mfma_f32_16x16x32_bf16 v[56:59], v[166:169], v[216:219], v[56:59]
	v_mfma_f32_16x16x32_bf16 v[52:55], v[176:179], v[216:219], v[52:55]
	v_mfma_f32_16x16x32_bf16 v[48:51], v[166:169], v[224:227], v[48:51]
	v_mfma_f32_16x16x32_bf16 v[44:47], v[176:179], v[224:227], v[44:47]
	v_mfma_f32_16x16x32_bf16 v[72:75], v[172:175], v[204:207], v[72:75]
	v_mfma_f32_16x16x32_bf16 v[68:71], v[180:183], v[204:207], v[68:71]
	v_mfma_f32_16x16x32_bf16 v[64:67], v[172:175], v[212:215], v[64:67]
	v_mfma_f32_16x16x32_bf16 v[60:63], v[180:183], v[212:215], v[60:63]
	v_mfma_f32_16x16x32_bf16 v[56:59], v[172:175], v[220:223], v[56:59]
	v_mfma_f32_16x16x32_bf16 v[52:55], v[180:183], v[220:223], v[52:55]
	v_mfma_f32_16x16x32_bf16 v[48:51], v[172:175], v[238:241], v[48:51]
	v_mfma_f32_16x16x32_bf16 v[44:47], v[180:183], v[238:241], v[44:47]
	v_mfma_f32_16x16x32_bf16 v[128:131], v[184:187], v[200:203], v[128:131]
	v_mfma_f32_16x16x32_bf16 v[124:127], v[192:195], v[200:203], v[124:127]
	v_mfma_f32_16x16x32_bf16 v[120:123], v[184:187], v[208:211], v[120:123]
	v_mfma_f32_16x16x32_bf16 v[116:119], v[192:195], v[208:211], v[116:119]
	v_mfma_f32_16x16x32_bf16 v[112:115], v[184:187], v[216:219], v[112:115]
	v_mfma_f32_16x16x32_bf16 v[108:111], v[192:195], v[216:219], v[108:111]
	v_mfma_f32_16x16x32_bf16 v[104:107], v[184:187], v[224:227], v[104:107]
	v_mfma_f32_16x16x32_bf16 v[100:103], v[192:195], v[224:227], v[100:103]
	v_mfma_f32_16x16x32_bf16 v[128:131], v[188:191], v[204:207], v[128:131]
	v_mfma_f32_16x16x32_bf16 v[124:127], v[196:199], v[204:207], v[124:127]
	v_mfma_f32_16x16x32_bf16 v[120:123], v[188:191], v[212:215], v[120:123]
	v_mfma_f32_16x16x32_bf16 v[116:119], v[196:199], v[212:215], v[116:119]
	v_mfma_f32_16x16x32_bf16 v[112:115], v[188:191], v[220:223], v[112:115]
	v_mfma_f32_16x16x32_bf16 v[108:111], v[196:199], v[220:223], v[108:111]
	v_mfma_f32_16x16x32_bf16 v[104:107], v[188:191], v[238:241], v[104:107]
	v_mfma_f32_16x16x32_bf16 v[100:103], v[196:199], v[238:241], v[100:103]
	s_barrier
; #define PG8_STAGE(bufoff, gbase, voff) do { _Pragma("unroll") for (int _i = 0; _i < 2; ++_i) \
;         __builtin_amdgcn_global_load_lds((const unsigned*)((const char*)(gbase) + (voff)[_i]), (PG8_LAS unsigned*)(lds + (bufoff) + ldsw + _i * 8192), 16, 0, 0); } while (0)
; #define PG8_LDA(dst, b, h) do { _Pragma("unroll") for (int m = 0; m < 4; ++m) _Pragma("unroll") for (int k = 0; k < 2; ++k) dst[m][k] = *(const PG8_LAS bf16x8*)(lds + PG8_SA(b, h) + aoff + m * 2048 + k * 1024); } while (0)
; #define PG8_MMA(ai, bj, At, Bt) do { __builtin_amdgcn_s_setprio(1); _Pragma("unroll") for (int m = 0; m < 4; ++m) _Pragma("unroll") for (int n = 0; n < 2; ++n) _Pragma("unroll") for (int k = 0; k < 2; ++k) \
;         acc[ai][bj][m][n] = __builtin_amdgcn_mfma_f32_16x16x32_bf16(Bt[n][k], At[m][k], acc[ai][bj][m][n], 0, 0, 0); __builtin_amdgcn_s_setprio(0); } while (0)
; #define PG8_WAIT_V(n) asm volatile("s_waitcnt vmcnt(" #n ")" ::: "memory")
; #define PG8_WAIT_L(n) asm volatile("s_waitcnt lgkmcnt(" #n ")" ::: "memory")
; #define PG8_BAR __builtin_amdgcn_s_barrier()
; #define PG8_SCHED __builtin_amdgcn_sched_barrier(0)
; template <class Epi, class Sched, bool ALIGN_EPI = false, bool SP2 = false>
; __device__ __forceinline__ void gemm_phase(PG8_LAS unsigned char* lds, const Gemm g, const Sched& S, const Epi& E, const int tid) {
;     ...
;             PG8_WAIT_V(8); PG8_WAIT_L(0); PG8_BAR; PG8_MMA(0, 0, At, B0); PG8_MMA(0, 1, At, B1); PG8_BAR; PG8_SCHED;
;             PG8_LDA(At, 1, 1); PG8_STAGE(PG8_SB(1, 0), b3, voffB); PG8_STAGE(PG8_SB(1, 1), b3 + hstep, voffB); PG8_STAGE(PG8_SA(1, 0), a3, voffA);
;             PG8_WAIT_V(8); PG8_WAIT_L(0); PG8_BAR; PG8_MMA(1, 0, At, B0); PG8_MMA(1, 1, At, B1); PG8_BAR; PG8_SCHED;
	s_add_i32 s36, s55, s43
	v_lshl_add_u64 v[146:147], v[146:147], 0, s[0:1]
	s_mov_b32 m0, s36
	ds_read_b128 v[200:203], v171 offset:49152
	ds_read_b128 v[204:207], v171 offset:50176
	ds_read_b128 v[208:211], v171 offset:51200
	ds_read_b128 v[212:215], v171 offset:52224
	ds_read_b128 v[216:219], v171 offset:53248
	ds_read_b128 v[220:223], v171 offset:54272
	ds_read_b128 v[224:227], v171 offset:55296
	ds_read_b128 v[238:241], v171 offset:56320
	global_load_lds_dwordx4 v[146:147], off
	s_add_i32 m0, s36, 0x2000
	s_add_u32 s26, s26, 0x40080
	v_lshl_add_u64 v[146:147], v[148:149], 0, s[0:1]
	s_addc_u32 s27, s27, 0
	s_add_i32 s36, s56, s43
	global_load_lds_dwordx4 v[146:147], off
	v_lshl_add_u64 v[146:147], s[26:27], 0, v[132:133]
	s_mov_b32 m0, s36
	s_nop 0
	global_load_lds_dwordx4 v[146:147], off
	v_lshl_add_u64 v[146:147], s[26:27], 0, v[136:137]
	s_add_i32 m0, s36, 0x2000
	s_nop 0
	global_load_lds_dwordx4 v[146:147], off
	v_lshl_add_u64 v[146:147], v[150:151], 0, s[0:1]
	s_mov_b32 m0, s48
	s_nop 0
	global_load_lds_dwordx4 v[146:147], off
	v_lshl_add_u64 v[146:147], v[242:243], 0, s[0:1]
	s_mov_b32 m0, s49
	s_nop 0
	global_load_lds_dwordx4 v[146:147], off
	s_waitcnt vmcnt(8)
	s_waitcnt lgkmcnt(0)
	s_barrier
	s_waitcnt lgkmcnt(0)
	v_mfma_f32_16x16x32_bf16 v[40:43], v[166:169], v[200:203], v[40:43]
	v_mfma_f32_16x16x32_bf16 v[36:39], v[176:179], v[200:203], v[36:39]
	v_mfma_f32_16x16x32_bf16 v[32:35], v[166:169], v[208:211], v[32:35]
	v_mfma_f32_16x16x32_bf16 v[28:31], v[176:179], v[208:211], v[28:31]
	v_mfma_f32_16x16x32_bf16 v[24:27], v[166:169], v[216:219], v[24:27]
	v_mfma_f32_16x16x32_bf16 v[20:23], v[176:179], v[216:219], v[20:23]
	v_mfma_f32_16x16x32_bf16 v[8:11], v[166:169], v[224:227], v[8:11]
	v_mfma_f32_16x16x32_bf16 v[4:7], v[176:179], v[224:227], v[4:7]
	v_mfma_f32_16x16x32_bf16 v[40:43], v[172:175], v[204:207], v[40:43]
	v_mfma_f32_16x16x32_bf16 v[36:39], v[180:183], v[204:207], v[36:39]
	v_mfma_f32_16x16x32_bf16 v[32:35], v[172:175], v[212:215], v[32:35]
	v_mfma_f32_16x16x32_bf16 v[28:31], v[180:183], v[212:215], v[28:31]
	v_mfma_f32_16x16x32_bf16 v[24:27], v[172:175], v[220:223], v[24:27]
	v_mfma_f32_16x16x32_bf16 v[20:23], v[180:183], v[220:223], v[20:23]
	v_mfma_f32_16x16x32_bf16 v[8:11], v[172:175], v[238:241], v[8:11]
	v_mfma_f32_16x16x32_bf16 v[4:7], v[180:183], v[238:241], v[4:7]
	v_mfma_f32_16x16x32_bf16 v[96:99], v[184:187], v[200:203], v[96:99]
	v_mfma_f32_16x16x32_bf16 v[92:95], v[192:195], v[200:203], v[92:95]
	v_mfma_f32_16x16x32_bf16 v[88:91], v[184:187], v[208:211], v[88:91]
	v_mfma_f32_16x16x32_bf16 v[84:87], v[192:195], v[208:211], v[84:87]
	v_mfma_f32_16x16x32_bf16 v[80:83], v[184:187], v[216:219], v[80:83]
	v_mfma_f32_16x16x32_bf16 v[76:79], v[192:195], v[216:219], v[76:79]
	v_mfma_f32_16x16x32_bf16 v[16:19], v[184:187], v[224:227], v[16:19]
	v_mfma_f32_16x16x32_bf16 v[12:15], v[192:195], v[224:227], v[12:15]
	v_mfma_f32_16x16x32_bf16 v[96:99], v[188:191], v[204:207], v[96:99]
	v_mfma_f32_16x16x32_bf16 v[92:95], v[196:199], v[204:207], v[92:95]
	v_mfma_f32_16x16x32_bf16 v[88:91], v[188:191], v[212:215], v[88:91]
	v_mfma_f32_16x16x32_bf16 v[84:87], v[196:199], v[212:215], v[84:87]
	v_mfma_f32_16x16x32_bf16 v[80:83], v[188:191], v[220:223], v[80:83]
	v_mfma_f32_16x16x32_bf16 v[76:79], v[196:199], v[220:223], v[76:79]
	v_mfma_f32_16x16x32_bf16 v[16:19], v[188:191], v[238:241], v[16:19]
	v_mfma_f32_16x16x32_bf16 v[12:15], v[196:199], v[238:241], v[12:15]
	s_barrier
	s_add_i32 s54, s54, 2
	s_add_u32 s2, s2, 0x100
	s_addc_u32 s3, s3, 0
	s_add_u32 s52, s52, 0x100
	s_addc_u32 s53, s53, 0
	s_cmp_gt_u32 s54, 13
	s_cbranch_scc0 .LBB0_293
	s_and_b64 vcc, exec, s[10:11]
	s_cbranch_vccz .LBB0_296
	s_barrier

; #define PG8_STAGE(bufoff, gbase, voff) do { _Pragma("unroll") for (int _i = 0; _i < 2; ++_i) \
;         __builtin_amdgcn_global_load_lds((const unsigned*)((const char*)(gbase) + (voff)[_i]), (PG8_LAS unsigned*)(lds + (bufoff) + ldsw + _i * 8192), 16, 0, 0); } while (0)
; #define PG8_LDA(dst, b, h) do { _Pragma("unroll") for (int m = 0; m < 4; ++m) _Pragma("unroll") for (int k = 0; k < 2; ++k) dst[m][k] = *(const PG8_LAS bf16x8*)(lds + PG8_SA(b, h) + aoff + m * 2048 + k * 1024); } while (0)
; #define PG8_LDB(dst, b, h) do { _Pragma("unroll") for (int n = 0; n < 2; ++n) _Pragma("unroll") for (int k = 0; k < 2; ++k) dst[n][k] = *(const PG8_LAS bf16x8*)(lds + PG8_SB(b, h) + boff + n * 2048 + k * 1024); } while (0)
; #define PG8_WAIT_V(n) asm volatile("s_waitcnt vmcnt(" #n ")" ::: "memory")
; #define PG8_WAIT_L(n) asm volatile("s_waitcnt lgkmcnt(" #n ")" ::: "memory")
; #define PG8_BAR __builtin_amdgcn_s_barrier()
; #define PG8_SCHED __builtin_amdgcn_sched_barrier(0)
; template <class Epi, class Sched, bool ALIGN_EPI = false, bool SP2 = false>
; __device__ __forceinline__ void gemm_phase(PG8_LAS unsigned char* lds, const Gemm g, const Sched& S, const Epi& E, const int tid) {
;     ...
;         const bool has_next = S.next(ui + 1, nxt);
;         const char* nA = has_next ? (const char*)g.A + (size_t)nxt.pm * tstep : cA; const char* nB = has_next ? (const char*)g.Bt + (size_t)nxt.pn * tstep : cB;
;         for (int t = 0; t < nt; t += 2) {
;             const bool last = (t == nt - 2);
;             const char* a1 = cA + (size_t)(t + 1) * kstep;
;             const char* a2 = last ? nA : cA + (size_t)(t + 2) * kstep; const char* b2 = last ? nB : cB + (size_t)(t + 2) * kstep;
;             const char* a3 = a2 + kstep; const char* b3 = b2 + kstep;
;             if (last && has_next) S.a_ready(nxt);
;             if constexpr (SP2) {
;             PG8_LDB(B0, 0, 0); PG8_LDB(B1, 0, 1); PG8_SCHED; PG8_LDA(At, 0, 0); PG8_STAGE(PG8_SA(1, 1), a1 + hstep, voffA);
;             PG8_WAIT_V(8); PG8_WAIT_L(0); PG8_BAR; PG8_MMA(0, 0, At, B0); PG8_MMA(0, 1, At, B1); PG8_BAR; PG8_SCHED;
;             PG8_LDA(At, 0, 1); PG8_STAGE(PG8_SB(0, 0), b2, voffB); PG8_STAGE(PG8_SB(0, 1), b2 + hstep, voffB); PG8_STAGE(PG8_SA(0, 0), a2, voffA);
;             PG8_WAIT_V(8); PG8_WAIT_L(0); PG8_BAR; PG8_MMA(1, 0, At, B0); PG8_MMA(1, 1, At, B1); PG8_BAR; PG8_SCHED;
.LBB0_476:
	s_add_i32 s80, s58, 2
	s_add_u32 s81, s6, 0x80
	s_addc_u32 s59, s7, 0
	s_add_i32 s87, 0, 0x10000
	s_cmp_eq_u32 s70, s58
	s_cselect_b32 s59, s55, s59
	s_cselect_b32 s58, s54, s81
	v_add_u32_e32 v144, s87, v184
	s_cselect_b32 s83, s57, s79
	s_cselect_b32 s82, s56, s78
	s_add_i32 s81, 0, 0x14000
	ds_read_b128 v[132:135], v144
	ds_read_b128 v[136:139], v144 offset:1024
	ds_read_b128 v[140:143], v144 offset:2048
	ds_read_b128 v[174:177], v144 offset:3072
	v_add_u32_e32 v144, s81, v184
	ds_read_b128 v[178:181], v144
	ds_read_b128 v[188:191], v144 offset:1024
	ds_read_b128 v[192:195], v144 offset:2048
	ds_read_b128 v[196:199], v144 offset:3072
	v_lshl_add_u64 v[144:145], s[6:7], 0, v[170:171]
	s_add_i32 m0, s62, 0xc000
	ds_read_b128 v[200:203], v186
	ds_read_b128 v[204:207], v186 offset:1024
	ds_read_b128 v[208:211], v186 offset:2048
	ds_read_b128 v[212:215], v186 offset:3072
	ds_read_b128 v[216:219], v186 offset:4096
	ds_read_b128 v[220:223], v186 offset:5120
	ds_read_b128 v[224:227], v186 offset:6144
	ds_read_b128 v[238:241], v186 offset:7168
	global_load_lds_dwordx4 v[144:145], off
	v_lshl_add_u64 v[144:145], s[6:7], 0, v[172:173]
	s_add_i32 m0, s62, 0xe000
	s_nop 0
	global_load_lds_dwordx4 v[144:145], off
	s_waitcnt vmcnt(8)
	s_waitcnt lgkmcnt(0)
	s_barrier
	s_waitcnt lgkmcnt(0)
	v_mfma_f32_16x16x32_bf16 v[128:131], v[132:135], v[200:203], v[128:131]
	v_mfma_f32_16x16x32_bf16 v[124:127], v[140:143], v[200:203], v[124:127]
	v_mfma_f32_16x16x32_bf16 v[112:115], v[132:135], v[208:211], v[112:115]
	v_mfma_f32_16x16x32_bf16 v[108:111], v[140:143], v[208:211], v[108:111]
	v_mfma_f32_16x16x32_bf16 v[96:99], v[132:135], v[216:219], v[96:99]
	v_mfma_f32_16x16x32_bf16 v[92:95], v[140:143], v[216:219], v[92:95]
	v_mfma_f32_16x16x32_bf16 v[80:83], v[132:135], v[224:227], v[80:83]
	v_mfma_f32_16x16x32_bf16 v[76:79], v[140:143], v[224:227], v[76:79]
	v_mfma_f32_16x16x32_bf16 v[128:131], v[136:139], v[204:207], v[128:131]
	v_mfma_f32_16x16x32_bf16 v[124:127], v[174:177], v[204:207], v[124:127]
	v_mfma_f32_16x16x32_bf16 v[112:115], v[136:139], v[212:215], v[112:115]
	v_mfma_f32_16x16x32_bf16 v[108:111], v[174:177], v[212:215], v[108:111]
	v_mfma_f32_16x16x32_bf16 v[96:99], v[136:139], v[220:223], v[96:99]
	v_mfma_f32_16x16x32_bf16 v[92:95], v[174:177], v[220:223], v[92:95]
	v_mfma_f32_16x16x32_bf16 v[80:83], v[136:139], v[238:241], v[80:83]
	v_mfma_f32_16x16x32_bf16 v[76:79], v[174:177], v[238:241], v[76:79]
	v_mfma_f32_16x16x32_bf16 v[120:123], v[178:181], v[200:203], v[120:123]
	v_mfma_f32_16x16x32_bf16 v[116:119], v[192:195], v[200:203], v[116:119]
	v_mfma_f32_16x16x32_bf16 v[104:107], v[178:181], v[208:211], v[104:107]
	v_mfma_f32_16x16x32_bf16 v[100:103], v[192:195], v[208:211], v[100:103]
	v_mfma_f32_16x16x32_bf16 v[88:91], v[178:181], v[216:219], v[88:91]
	v_mfma_f32_16x16x32_bf16 v[84:87], v[192:195], v[216:219], v[84:87]
	v_mfma_f32_16x16x32_bf16 v[72:75], v[178:181], v[224:227], v[72:75]
	v_mfma_f32_16x16x32_bf16 v[68:71], v[192:195], v[224:227], v[68:71]
	v_mfma_f32_16x16x32_bf16 v[120:123], v[188:191], v[204:207], v[120:123]
	v_mfma_f32_16x16x32_bf16 v[116:119], v[196:199], v[204:207], v[116:119]
	v_mfma_f32_16x16x32_bf16 v[104:107], v[188:191], v[212:215], v[104:107]
	v_mfma_f32_16x16x32_bf16 v[100:103], v[196:199], v[212:215], v[100:103]
	v_mfma_f32_16x16x32_bf16 v[88:91], v[188:191], v[220:223], v[88:91]
	v_mfma_f32_16x16x32_bf16 v[84:87], v[196:199], v[220:223], v[84:87]
	v_mfma_f32_16x16x32_bf16 v[72:75], v[188:191], v[238:241], v[72:75]
	v_mfma_f32_16x16x32_bf16 v[68:71], v[196:199], v[238:241], v[68:71]
	s_barrier
	s_add_i32 s87, s87, s61
	v_lshl_add_u64 v[144:145], s[82:83], 0, v[146:147]
	s_mov_b32 m0, s87
	ds_read_b128 v[200:203], v186 offset:16384
	ds_read_b128 v[204:207], v186 offset:17408
	ds_read_b128 v[208:211], v186 offset:18432
	ds_read_b128 v[212:215], v186 offset:19456
	ds_read_b128 v[216:219], v186 offset:20480
	ds_read_b128 v[220:223], v186 offset:21504
	ds_read_b128 v[224:227], v186 offset:22528
	ds_read_b128 v[238:241], v186 offset:23552
	global_load_lds_dwordx4 v[144:145], off
	s_add_i32 m0, s87, 0x2000
	v_lshl_add_u64 v[242:243], s[82:83], 0, v[168:169]
	s_add_u32 s82, s82, s14
	s_addc_u32 s83, s83, 0
	s_add_i32 s81, s81, s61
	global_load_lds_dwordx4 v[242:243], off
	v_lshl_add_u64 v[244:245], s[82:83], 0, v[146:147]
	s_mov_b32 m0, s81
	v_lshl_add_u64 v[246:247], s[82:83], 0, v[168:169]
	global_load_lds_dwordx4 v[244:245], off
	s_add_i32 m0, s81, 0x2000
	v_lshl_add_u64 v[248:249], s[58:59], 0, v[0:1]
	global_load_lds_dwordx4 v[246:247], off
	s_mov_b32 m0, s62
	v_lshl_add_u64 v[148:149], s[58:59], 0, v[166:167]
	global_load_lds_dwordx4 v[248:249], off
	s_mov_b32 m0, s63
	s_nop 0
	global_load_lds_dwordx4 v[148:149], off
	s_waitcnt vmcnt(8)
	s_waitcnt lgkmcnt(0)
	s_barrier
; #define PG8_STAGE(bufoff, gbase, voff) do { _Pragma("unroll") for (int _i = 0; _i < 2; ++_i) \
;         __builtin_amdgcn_global_load_lds((const unsigned*)((const char*)(gbase) + (voff)[_i]), (PG8_LAS unsigned*)(lds + (bufoff) + ldsw + _i * 8192), 16, 0, 0); } while (0)
; #define PG8_LDA(dst, b, h) do { _Pragma("unroll") for (int m = 0; m < 4; ++m) _Pragma("unroll") for (int k = 0; k < 2; ++k) dst[m][k] = *(const PG8_LAS bf16x8*)(lds + PG8_SA(b, h) + aoff + m * 2048 + k * 1024); } while (0)
; #define PG8_LDB(dst, b, h) do { _Pragma("unroll") for (int n = 0; n < 2; ++n) _Pragma("unroll") for (int k = 0; k < 2; ++k) dst[n][k] = *(const PG8_LAS bf16x8*)(lds + PG8_SB(b, h) + boff + n * 2048 + k * 1024); } while (0)
; #define PG8_MMA(ai, bj, At, Bt) do { __builtin_amdgcn_s_setprio(1); _Pragma("unroll") for (int m = 0; m < 4; ++m) _Pragma("unroll") for (int n = 0; n < 2; ++n) _Pragma("unroll") for (int k = 0; k < 2; ++k) \
;         acc[ai][bj][m][n] = __builtin_amdgcn_mfma_f32_16x16x32_bf16(Bt[n][k], At[m][k], acc[ai][bj][m][n], 0, 0, 0); __builtin_amdgcn_s_setprio(0); } while (0)
; #define PG8_WAIT_V(n) asm volatile("s_waitcnt vmcnt(" #n ")" ::: "memory")
; #define PG8_WAIT_L(n) asm volatile("s_waitcnt lgkmcnt(" #n ")" ::: "memory")
; #define PG8_BAR __builtin_amdgcn_s_barrier()
; #define PG8_SCHED __builtin_amdgcn_sched_barrier(0)
; template <class Epi, class Sched, bool ALIGN_EPI = false, bool SP2 = false>
; __device__ __forceinline__ void gemm_phase(PG8_LAS unsigned char* lds, const Gemm g, const Sched& S, const Epi& E, const int tid) {
;     ...
;             PG8_WAIT_V(8); PG8_WAIT_L(0); PG8_BAR; PG8_MMA(1, 0, At, B0); PG8_MMA(1, 1, At, B1); PG8_BAR; PG8_SCHED;
;             PG8_LDB(B0, 1, 0); PG8_LDB(B1, 1, 1); PG8_SCHED; PG8_LDA(At, 1, 0); PG8_STAGE(PG8_SA(0, 1), a2 + hstep, voffA);
;             PG8_WAIT_V(8); PG8_WAIT_L(0); PG8_BAR; PG8_MMA(0, 0, At, B0); PG8_MMA(0, 1, At, B1); PG8_BAR; PG8_SCHED;
	s_waitcnt lgkmcnt(0)
	v_mfma_f32_16x16x32_bf16 v[64:67], v[132:135], v[200:203], v[64:67]
	v_mfma_f32_16x16x32_bf16 v[60:63], v[140:143], v[200:203], v[60:63]
	v_mfma_f32_16x16x32_bf16 v[48:51], v[132:135], v[208:211], v[48:51]
	v_mfma_f32_16x16x32_bf16 v[44:47], v[140:143], v[208:211], v[44:47]
	v_mfma_f32_16x16x32_bf16 v[32:35], v[132:135], v[216:219], v[32:35]
	v_mfma_f32_16x16x32_bf16 v[28:31], v[140:143], v[216:219], v[28:31]
	v_mfma_f32_16x16x32_bf16 v[16:19], v[132:135], v[224:227], v[16:19]
	v_mfma_f32_16x16x32_bf16 v[12:15], v[140:143], v[224:227], v[12:15]
	v_mfma_f32_16x16x32_bf16 v[64:67], v[136:139], v[204:207], v[64:67]
	v_mfma_f32_16x16x32_bf16 v[60:63], v[174:177], v[204:207], v[60:63]
	v_mfma_f32_16x16x32_bf16 v[48:51], v[136:139], v[212:215], v[48:51]
	v_mfma_f32_16x16x32_bf16 v[44:47], v[174:177], v[212:215], v[44:47]
	v_mfma_f32_16x16x32_bf16 v[32:35], v[136:139], v[220:223], v[32:35]
	v_mfma_f32_16x16x32_bf16 v[28:31], v[174:177], v[220:223], v[28:31]
	v_mfma_f32_16x16x32_bf16 v[16:19], v[136:139], v[238:241], v[16:19]
	v_mfma_f32_16x16x32_bf16 v[12:15], v[174:177], v[238:241], v[12:15]
	v_mfma_f32_16x16x32_bf16 v[56:59], v[178:181], v[200:203], v[56:59]
	v_mfma_f32_16x16x32_bf16 v[52:55], v[192:195], v[200:203], v[52:55]
	v_mfma_f32_16x16x32_bf16 v[40:43], v[178:181], v[208:211], v[40:43]
	v_mfma_f32_16x16x32_bf16 v[36:39], v[192:195], v[208:211], v[36:39]
	v_mfma_f32_16x16x32_bf16 v[24:27], v[178:181], v[216:219], v[24:27]
	v_mfma_f32_16x16x32_bf16 v[20:23], v[192:195], v[216:219], v[20:23]
	v_mfma_f32_16x16x32_bf16 v[8:11], v[178:181], v[224:227], v[8:11]
	v_mfma_f32_16x16x32_bf16 v[4:7], v[192:195], v[224:227], v[4:7]
	v_mfma_f32_16x16x32_bf16 v[56:59], v[188:191], v[204:207], v[56:59]
	v_mfma_f32_16x16x32_bf16 v[52:55], v[196:199], v[204:207], v[52:55]
	v_mfma_f32_16x16x32_bf16 v[40:43], v[188:191], v[212:215], v[40:43]
	v_mfma_f32_16x16x32_bf16 v[36:39], v[196:199], v[212:215], v[36:39]
	v_mfma_f32_16x16x32_bf16 v[24:27], v[188:191], v[220:223], v[24:27]
	v_mfma_f32_16x16x32_bf16 v[20:23], v[196:199], v[220:223], v[20:23]
	v_mfma_f32_16x16x32_bf16 v[8:11], v[188:191], v[238:241], v[8:11]
	v_mfma_f32_16x16x32_bf16 v[4:7], v[196:199], v[238:241], v[4:7]
	s_barrier
	s_add_i32 s81, 0, 0x18000
	v_add_u32_e32 v150, s81, v184
	s_add_i32 s82, 0, 0x1c000
	ds_read_b128 v[132:135], v150
	ds_read_b128 v[136:139], v150 offset:1024
	ds_read_b128 v[140:143], v150 offset:2048
	ds_read_b128 v[174:177], v150 offset:3072
	v_add_u32_e32 v150, s82, v184
	ds_read_b128 v[178:181], v150
	ds_read_b128 v[188:191], v150 offset:1024
	ds_read_b128 v[192:195], v150 offset:2048
	ds_read_b128 v[196:199], v150 offset:3072
	s_add_u32 s58, s58, s14
	s_addc_u32 s59, s59, 0
	s_mov_b32 m0, s64
	v_lshl_add_u64 v[150:151], s[58:59], 0, v[0:1]
	ds_read_b128 v[200:203], v186 offset:32768
	ds_read_b128 v[204:207], v186 offset:33792
	ds_read_b128 v[208:211], v186 offset:34816
	ds_read_b128 v[212:215], v186 offset:35840
	ds_read_b128 v[216:219], v186 offset:36864
	ds_read_b128 v[220:223], v186 offset:37888
	ds_read_b128 v[224:227], v186 offset:38912
	ds_read_b128 v[238:241], v186 offset:39936
	global_load_lds_dwordx4 v[150:151], off
	v_lshl_add_u64 v[150:151], s[58:59], 0, v[166:167]
	s_mov_b32 m0, s65
	s_nop 0
	global_load_lds_dwordx4 v[150:151], off
	s_waitcnt vmcnt(8)
	s_waitcnt lgkmcnt(0)
	s_barrier
	s_waitcnt lgkmcnt(0)
	v_mfma_f32_16x16x32_bf16 v[128:131], v[132:135], v[200:203], v[128:131]
	v_mfma_f32_16x16x32_bf16 v[124:127], v[140:143], v[200:203], v[124:127]
	v_mfma_f32_16x16x32_bf16 v[112:115], v[132:135], v[208:211], v[112:115]
	v_mfma_f32_16x16x32_bf16 v[108:111], v[140:143], v[208:211], v[108:111]
	v_mfma_f32_16x16x32_bf16 v[96:99], v[132:135], v[216:219], v[96:99]
	v_mfma_f32_16x16x32_bf16 v[92:95], v[140:143], v[216:219], v[92:95]
	v_mfma_f32_16x16x32_bf16 v[80:83], v[132:135], v[224:227], v[80:83]
	v_mfma_f32_16x16x32_bf16 v[76:79], v[140:143], v[224:227], v[76:79]
	v_mfma_f32_16x16x32_bf16 v[128:131], v[136:139], v[204:207], v[128:131]
	v_mfma_f32_16x16x32_bf16 v[124:127], v[174:177], v[204:207], v[124:127]
	v_mfma_f32_16x16x32_bf16 v[112:115], v[136:139], v[212:215], v[112:115]
	v_mfma_f32_16x16x32_bf16 v[108:111], v[174:177], v[212:215], v[108:111]
	v_mfma_f32_16x16x32_bf16 v[96:99], v[136:139], v[220:223], v[96:99]
	v_mfma_f32_16x16x32_bf16 v[92:95], v[174:177], v[220:223], v[92:95]
	v_mfma_f32_16x16x32_bf16 v[80:83], v[136:139], v[238:241], v[80:83]
	v_mfma_f32_16x16x32_bf16 v[76:79], v[174:177], v[238:241], v[76:79]
	v_mfma_f32_16x16x32_bf16 v[120:123], v[178:181], v[200:203], v[120:123]
	v_mfma_f32_16x16x32_bf16 v[116:119], v[192:195], v[200:203], v[116:119]
	v_mfma_f32_16x16x32_bf16 v[104:107], v[178:181], v[208:211], v[104:107]
	v_mfma_f32_16x16x32_bf16 v[100:103], v[192:195], v[208:211], v[100:103]
	v_mfma_f32_16x16x32_bf16 v[88:91], v[178:181], v[216:219], v[88:91]
	v_mfma_f32_16x16x32_bf16 v[84:87], v[192:195], v[216:219], v[84:87]
	v_mfma_f32_16x16x32_bf16 v[72:75], v[178:181], v[224:227], v[72:75]
	v_mfma_f32_16x16x32_bf16 v[68:71], v[192:195], v[224:227], v[68:71]
	v_mfma_f32_16x16x32_bf16 v[120:123], v[188:191], v[204:207], v[120:123]
	v_mfma_f32_16x16x32_bf16 v[116:119], v[196:199], v[204:207], v[116:119]
	v_mfma_f32_16x16x32_bf16 v[104:107], v[188:191], v[212:215], v[104:107]
	v_mfma_f32_16x16x32_bf16 v[100:103], v[196:199], v[212:215], v[100:103]
	v_mfma_f32_16x16x32_bf16 v[88:91], v[188:191], v[220:223], v[88:91]
	v_mfma_f32_16x16x32_bf16 v[84:87], v[196:199], v[220:223], v[84:87]
	v_mfma_f32_16x16x32_bf16 v[72:75], v[188:191], v[238:241], v[72:75]
	v_mfma_f32_16x16x32_bf16 v[68:71], v[196:199], v[238:241], v[68:71]
	s_barrier
; #define PG8_STAGE(bufoff, gbase, voff) do { _Pragma("unroll") for (int _i = 0; _i < 2; ++_i) \
;         __builtin_amdgcn_global_load_lds((const unsigned*)((const char*)(gbase) + (voff)[_i]), (PG8_LAS unsigned*)(lds + (bufoff) + ldsw + _i * 8192), 16, 0, 0); } while (0)
; #define PG8_LDA(dst, b, h) do { _Pragma("unroll") for (int m = 0; m < 4; ++m) _Pragma("unroll") for (int k = 0; k < 2; ++k) dst[m][k] = *(const PG8_LAS bf16x8*)(lds + PG8_SA(b, h) + aoff + m * 2048 + k * 1024); } while (0)
; #define PG8_MMA(ai, bj, At, Bt) do { __builtin_amdgcn_s_setprio(1); _Pragma("unroll") for (int m = 0; m < 4; ++m) _Pragma("unroll") for (int n = 0; n < 2; ++n) _Pragma("unroll") for (int k = 0; k < 2; ++k) \
;         acc[ai][bj][m][n] = __builtin_amdgcn_mfma_f32_16x16x32_bf16(Bt[n][k], At[m][k], acc[ai][bj][m][n], 0, 0, 0); __builtin_amdgcn_s_setprio(0); } while (0)
; #define PG8_WAIT_V(n) asm volatile("s_waitcnt vmcnt(" #n ")" ::: "memory")
; #define PG8_WAIT_L(n) asm volatile("s_waitcnt lgkmcnt(" #n ")" ::: "memory")
; #define PG8_BAR __builtin_amdgcn_s_barrier()
; #define PG8_SCHED __builtin_amdgcn_sched_barrier(0)
; template <class Epi, class Sched, bool ALIGN_EPI = false, bool SP2 = false>
; __device__ __forceinline__ void gemm_phase(PG8_LAS unsigned char* lds, const Gemm g, const Sched& S, const Epi& E, const int tid) {
;     ...
;             PG8_LDA(At, 1, 1); PG8_STAGE(PG8_SB(1, 0), b3, voffB); PG8_STAGE(PG8_SB(1, 1), b3 + hstep, voffB); PG8_STAGE(PG8_SA(1, 0), a3, voffA);
;             PG8_WAIT_V(8); PG8_WAIT_L(0); PG8_BAR; PG8_MMA(1, 0, At, B0); PG8_MMA(1, 1, At, B1); PG8_BAR; PG8_SCHED;
;     ...
;         if constexpr (ALIGN_EPI) { if (wr == 0) PG8_BAR; }
	s_add_i32 s58, s81, s61
	v_lshl_add_u64 v[144:145], v[144:145], 0, s[0:1]
	s_mov_b32 m0, s58
	ds_read_b128 v[200:203], v186 offset:49152
	ds_read_b128 v[204:207], v186 offset:50176
	ds_read_b128 v[208:211], v186 offset:51200
	ds_read_b128 v[212:215], v186 offset:52224
	ds_read_b128 v[216:219], v186 offset:53248
	ds_read_b128 v[220:223], v186 offset:54272
	ds_read_b128 v[224:227], v186 offset:55296
	ds_read_b128 v[238:241], v186 offset:56320
	global_load_lds_dwordx4 v[144:145], off
	v_lshl_add_u64 v[144:145], v[242:243], 0, s[0:1]
	s_add_i32 m0, s58, 0x2000
	s_add_i32 s58, s82, s61
	global_load_lds_dwordx4 v[144:145], off
	v_lshl_add_u64 v[144:145], v[244:245], 0, s[0:1]
	s_mov_b32 m0, s58
	s_nop 0
	global_load_lds_dwordx4 v[144:145], off
	v_lshl_add_u64 v[144:145], v[246:247], 0, s[0:1]
	s_add_i32 m0, s58, 0x2000
	s_nop 0
	global_load_lds_dwordx4 v[144:145], off
	v_lshl_add_u64 v[144:145], v[248:249], 0, s[0:1]
	s_mov_b32 m0, s66
	s_nop 0
	global_load_lds_dwordx4 v[144:145], off
	v_lshl_add_u64 v[144:145], v[148:149], 0, s[0:1]
	s_mov_b32 m0, s67
	s_nop 0
	global_load_lds_dwordx4 v[144:145], off
	s_waitcnt vmcnt(8)
	s_waitcnt lgkmcnt(0)
	s_barrier
	s_waitcnt lgkmcnt(0)
	v_mfma_f32_16x16x32_bf16 v[64:67], v[132:135], v[200:203], v[64:67]
	v_mfma_f32_16x16x32_bf16 v[60:63], v[140:143], v[200:203], v[60:63]
	v_mfma_f32_16x16x32_bf16 v[48:51], v[132:135], v[208:211], v[48:51]
	v_mfma_f32_16x16x32_bf16 v[44:47], v[140:143], v[208:211], v[44:47]
	v_mfma_f32_16x16x32_bf16 v[32:35], v[132:135], v[216:219], v[32:35]
	v_mfma_f32_16x16x32_bf16 v[28:31], v[140:143], v[216:219], v[28:31]
	v_mfma_f32_16x16x32_bf16 v[16:19], v[132:135], v[224:227], v[16:19]
	v_mfma_f32_16x16x32_bf16 v[12:15], v[140:143], v[224:227], v[12:15]
	v_mfma_f32_16x16x32_bf16 v[64:67], v[136:139], v[204:207], v[64:67]
	v_mfma_f32_16x16x32_bf16 v[60:63], v[174:177], v[204:207], v[60:63]
	v_mfma_f32_16x16x32_bf16 v[48:51], v[136:139], v[212:215], v[48:51]
	v_mfma_f32_16x16x32_bf16 v[44:47], v[174:177], v[212:215], v[44:47]
	v_mfma_f32_16x16x32_bf16 v[32:35], v[136:139], v[220:223], v[32:35]
	v_mfma_f32_16x16x32_bf16 v[28:31], v[174:177], v[220:223], v[28:31]
	v_mfma_f32_16x16x32_bf16 v[16:19], v[136:139], v[238:241], v[16:19]
	v_mfma_f32_16x16x32_bf16 v[12:15], v[174:177], v[238:241], v[12:15]
	v_mfma_f32_16x16x32_bf16 v[56:59], v[178:181], v[200:203], v[56:59]
	v_mfma_f32_16x16x32_bf16 v[52:55], v[192:195], v[200:203], v[52:55]
	v_mfma_f32_16x16x32_bf16 v[40:43], v[178:181], v[208:211], v[40:43]
	v_mfma_f32_16x16x32_bf16 v[36:39], v[192:195], v[208:211], v[36:39]
	v_mfma_f32_16x16x32_bf16 v[24:27], v[178:181], v[216:219], v[24:27]
	v_mfma_f32_16x16x32_bf16 v[20:23], v[192:195], v[216:219], v[20:23]
	v_mfma_f32_16x16x32_bf16 v[8:11], v[178:181], v[224:227], v[8:11]
	v_mfma_f32_16x16x32_bf16 v[4:7], v[192:195], v[224:227], v[4:7]
	v_mfma_f32_16x16x32_bf16 v[56:59], v[188:191], v[204:207], v[56:59]
	v_mfma_f32_16x16x32_bf16 v[52:55], v[196:199], v[204:207], v[52:55]
	v_mfma_f32_16x16x32_bf16 v[40:43], v[188:191], v[212:215], v[40:43]
	v_mfma_f32_16x16x32_bf16 v[36:39], v[196:199], v[212:215], v[36:39]
	v_mfma_f32_16x16x32_bf16 v[24:27], v[188:191], v[220:223], v[24:27]
	v_mfma_f32_16x16x32_bf16 v[20:23], v[196:199], v[220:223], v[20:23]
	v_mfma_f32_16x16x32_bf16 v[8:11], v[188:191], v[238:241], v[8:11]
	v_mfma_f32_16x16x32_bf16 v[4:7], v[196:199], v[238:241], v[4:7]
	s_barrier
	s_add_u32 s6, s6, 0x100
	s_addc_u32 s7, s7, 0
	s_add_u32 s78, s78, 0x100
	s_addc_u32 s79, s79, 0
	s_cmp_ge_u32 s80, s69
	s_mov_b32 s58, s80
	s_cbranch_scc0 .LBB0_476
	s_and_b64 vcc, exec, s[50:51]
	s_cbranch_vccz .LBB0_479
	s_barrier

; #define PG8_STAGE(bufoff, gbase, voff) do { _Pragma("unroll") for (int _i = 0; _i < 2; ++_i) \
;         __builtin_amdgcn_global_load_lds((const unsigned*)((const char*)(gbase) + (voff)[_i]), (PG8_LAS unsigned*)(lds + (bufoff) + ldsw + _i * 8192), 16, 0, 0); } while (0)
; #define PG8_LDA(dst, b, h) do { _Pragma("unroll") for (int m = 0; m < 4; ++m) _Pragma("unroll") for (int k = 0; k < 2; ++k) dst[m][k] = *(const PG8_LAS bf16x8*)(lds + PG8_SA(b, h) + aoff + m * 2048 + k * 1024); } while (0)
; #define PG8_LDB(dst, b, h) do { _Pragma("unroll") for (int n = 0; n < 2; ++n) _Pragma("unroll") for (int k = 0; k < 2; ++k) dst[n][k] = *(const PG8_LAS bf16x8*)(lds + PG8_SB(b, h) + boff + n * 2048 + k * 1024); } while (0)
; #define PG8_MMA(ai, bj, At, Bt) do { __builtin_amdgcn_s_setprio(1); _Pragma("unroll") for (int m = 0; m < 4; ++m) _Pragma("unroll") for (int n = 0; n < 2; ++n) _Pragma("unroll") for (int k = 0; k < 2; ++k) \
;         acc[ai][bj][m][n] = __builtin_amdgcn_mfma_f32_16x16x32_bf16(Bt[n][k], At[m][k], acc[ai][bj][m][n], 0, 0, 0); __builtin_amdgcn_s_setprio(0); } while (0)
; #define PG8_WAIT_V(n) asm volatile("s_waitcnt vmcnt(" #n ")" ::: "memory")
; #define PG8_WAIT_L(n) asm volatile("s_waitcnt lgkmcnt(" #n ")" ::: "memory")
; #define PG8_BAR __builtin_amdgcn_s_barrier()
; #define PG8_SCHED __builtin_amdgcn_sched_barrier(0)
; template <class Epi, class Sched, bool ALIGN_EPI = false, bool SP2 = false>
; __device__ __forceinline__ void gemm_phase(PG8_LAS unsigned char* lds, const Gemm g, const Sched& S, const Epi& E, const int tid) {
;     ...
;             const bool last = (t == nt - 2);
;             const char* a1 = cA + (size_t)(t + 1) * kstep;
;             const char* a2 = last ? nA : cA + (size_t)(t + 2) * kstep; const char* b2 = last ? nB : cB + (size_t)(t + 2) * kstep;
;             const char* a3 = a2 + kstep; const char* b3 = b2 + kstep;
;             if (last && has_next) S.a_ready(nxt);
;             if constexpr (SP2) {
;             PG8_LDB(B0, 0, 0); PG8_LDB(B1, 0, 1); PG8_SCHED; PG8_LDA(At, 0, 0); PG8_STAGE(PG8_SA(1, 1), a1 + hstep, voffA);
;             PG8_WAIT_V(8); PG8_WAIT_L(0); PG8_BAR; PG8_MMA(0, 0, At, B0); PG8_MMA(0, 1, At, B1); PG8_BAR; PG8_SCHED;
;             PG8_LDA(At, 0, 1); PG8_STAGE(PG8_SB(0, 0), b2, voffB); PG8_STAGE(PG8_SB(0, 1), b2 + hstep, voffB); PG8_STAGE(PG8_SA(0, 0), a2, voffA);
.LBB0_522:
	s_add_u32 s20, s18, 0xfffc0080
	s_addc_u32 s21, s19, -1
	s_add_i32 s52, 0, 0x10000
	s_cmp_eq_u32 s51, 12
	s_cselect_b32 s23, s13, s21
	s_cselect_b32 s22, s47, s20
	v_add_u32_e32 v148, s52, v146
	s_cselect_b32 s21, s11, s50
	s_cselect_b32 s20, s48, s49
	s_add_i32 s54, 0, 0x14000
	ds_read_b128 v[142:145], v148
	ds_read_b128 v[166:169], v148 offset:1024
	ds_read_b128 v[170:173], v148 offset:2048
	ds_read_b128 v[174:177], v148 offset:3072
	v_add_u32_e32 v148, s54, v146
	ds_read_b128 v[178:181], v148
	ds_read_b128 v[182:185], v148 offset:1024
	ds_read_b128 v[186:189], v148 offset:2048
	ds_read_b128 v[190:193], v148 offset:3072
	v_lshl_add_u64 v[226:227], s[18:19], 0, v[138:139]
	s_add_i32 m0, s38, 0xc000
	ds_read_b128 v[194:197], v153
	ds_read_b128 v[198:201], v153 offset:1024
	ds_read_b128 v[202:205], v153 offset:2048
	ds_read_b128 v[206:209], v153 offset:3072
	ds_read_b128 v[210:213], v153 offset:4096
	ds_read_b128 v[214:217], v153 offset:5120
	ds_read_b128 v[218:221], v153 offset:6144
	ds_read_b128 v[222:225], v153 offset:7168
	global_load_lds_dwordx4 v[226:227], off
	v_lshl_add_u64 v[226:227], s[18:19], 0, v[140:141]
	s_add_i32 m0, s38, 0xe000
	s_nop 0
	global_load_lds_dwordx4 v[226:227], off
	s_waitcnt vmcnt(8)
	s_waitcnt lgkmcnt(0)
	s_barrier
	s_waitcnt lgkmcnt(0)
	v_mfma_f32_16x16x32_bf16 v[128:131], v[142:145], v[194:197], v[128:131]
	v_mfma_f32_16x16x32_bf16 v[120:123], v[170:173], v[194:197], v[120:123]
	v_mfma_f32_16x16x32_bf16 v[112:115], v[142:145], v[202:205], v[112:115]
	v_mfma_f32_16x16x32_bf16 v[104:107], v[170:173], v[202:205], v[104:107]
	v_mfma_f32_16x16x32_bf16 v[96:99], v[142:145], v[210:213], v[96:99]
	v_mfma_f32_16x16x32_bf16 v[88:91], v[170:173], v[210:213], v[88:91]
	v_mfma_f32_16x16x32_bf16 v[80:83], v[142:145], v[218:221], v[80:83]
	v_mfma_f32_16x16x32_bf16 v[72:75], v[170:173], v[218:221], v[72:75]
	v_mfma_f32_16x16x32_bf16 v[128:131], v[166:169], v[198:201], v[128:131]
	v_mfma_f32_16x16x32_bf16 v[120:123], v[174:177], v[198:201], v[120:123]
	v_mfma_f32_16x16x32_bf16 v[112:115], v[166:169], v[206:209], v[112:115]
	v_mfma_f32_16x16x32_bf16 v[104:107], v[174:177], v[206:209], v[104:107]
	v_mfma_f32_16x16x32_bf16 v[96:99], v[166:169], v[214:217], v[96:99]
	v_mfma_f32_16x16x32_bf16 v[88:91], v[174:177], v[214:217], v[88:91]
	v_mfma_f32_16x16x32_bf16 v[80:83], v[166:169], v[222:225], v[80:83]
	v_mfma_f32_16x16x32_bf16 v[72:75], v[174:177], v[222:225], v[72:75]
	v_mfma_f32_16x16x32_bf16 v[124:127], v[178:181], v[194:197], v[124:127]
	v_mfma_f32_16x16x32_bf16 v[116:119], v[186:189], v[194:197], v[116:119]
	v_mfma_f32_16x16x32_bf16 v[108:111], v[178:181], v[202:205], v[108:111]
	v_mfma_f32_16x16x32_bf16 v[100:103], v[186:189], v[202:205], v[100:103]
	v_mfma_f32_16x16x32_bf16 v[92:95], v[178:181], v[210:213], v[92:95]
	v_mfma_f32_16x16x32_bf16 v[84:87], v[186:189], v[210:213], v[84:87]
	v_mfma_f32_16x16x32_bf16 v[76:79], v[178:181], v[218:221], v[76:79]
	v_mfma_f32_16x16x32_bf16 v[68:71], v[186:189], v[218:221], v[68:71]
	v_mfma_f32_16x16x32_bf16 v[124:127], v[182:185], v[198:201], v[124:127]
	v_mfma_f32_16x16x32_bf16 v[116:119], v[190:193], v[198:201], v[116:119]
	v_mfma_f32_16x16x32_bf16 v[108:111], v[182:185], v[206:209], v[108:111]
	v_mfma_f32_16x16x32_bf16 v[100:103], v[190:193], v[206:209], v[100:103]
	v_mfma_f32_16x16x32_bf16 v[92:95], v[182:185], v[214:217], v[92:95]
	v_mfma_f32_16x16x32_bf16 v[84:87], v[190:193], v[214:217], v[84:87]
	v_mfma_f32_16x16x32_bf16 v[76:79], v[182:185], v[222:225], v[76:79]
	v_mfma_f32_16x16x32_bf16 v[68:71], v[190:193], v[222:225], v[68:71]
	s_barrier
	s_add_i32 s52, s52, s37
	v_lshl_add_u64 v[226:227], s[20:21], 0, v[134:135]
	s_mov_b32 m0, s52
	ds_read_b128 v[194:197], v153 offset:16384
	ds_read_b128 v[198:201], v153 offset:17408
	ds_read_b128 v[202:205], v153 offset:18432
	ds_read_b128 v[206:209], v153 offset:19456
	ds_read_b128 v[210:213], v153 offset:20480
	ds_read_b128 v[214:217], v153 offset:21504
	ds_read_b128 v[218:221], v153 offset:22528
	ds_read_b128 v[222:225], v153 offset:23552
	global_load_lds_dwordx4 v[226:227], off
	s_add_i32 m0, s52, 0x2000
	s_add_u32 s52, s20, 0x40000
	v_lshl_add_u64 v[238:239], s[20:21], 0, v[0:1]
	s_addc_u32 s53, s21, 0
	s_add_i32 s54, s54, s37
	global_load_lds_dwordx4 v[238:239], off
	v_lshl_add_u64 v[240:241], s[52:53], 0, v[134:135]
	s_mov_b32 m0, s54
	v_lshl_add_u64 v[242:243], s[22:23], 0, v[132:133]
	global_load_lds_dwordx4 v[240:241], off
	v_lshl_add_u64 v[240:241], s[52:53], 0, v[0:1]
	s_add_i32 m0, s54, 0x2000
	s_nop 0
	global_load_lds_dwordx4 v[240:241], off
	v_lshl_add_u64 v[240:241], s[22:23], 0, v[136:137]
	s_mov_b32 m0, s38
	s_nop 0
	global_load_lds_dwordx4 v[240:241], off
	s_mov_b32 m0, s39
	s_nop 0
	global_load_lds_dwordx4 v[242:243], off
	s_waitcnt vmcnt(8)
	s_waitcnt lgkmcnt(0)
	s_barrier
; #define PG8_STAGE(bufoff, gbase, voff) do { _Pragma("unroll") for (int _i = 0; _i < 2; ++_i) \
;         __builtin_amdgcn_global_load_lds((const unsigned*)((const char*)(gbase) + (voff)[_i]), (PG8_LAS unsigned*)(lds + (bufoff) + ldsw + _i * 8192), 16, 0, 0); } while (0)
; #define PG8_LDA(dst, b, h) do { _Pragma("unroll") for (int m = 0; m < 4; ++m) _Pragma("unroll") for (int k = 0; k < 2; ++k) dst[m][k] = *(const PG8_LAS bf16x8*)(lds + PG8_SA(b, h) + aoff + m * 2048 + k * 1024); } while (0)
; #define PG8_LDB(dst, b, h) do { _Pragma("unroll") for (int n = 0; n < 2; ++n) _Pragma("unroll") for (int k = 0; k < 2; ++k) dst[n][k] = *(const PG8_LAS bf16x8*)(lds + PG8_SB(b, h) + boff + n * 2048 + k * 1024); } while (0)
; #define PG8_MMA(ai, bj, At, Bt) do { __builtin_amdgcn_s_setprio(1); _Pragma("unroll") for (int m = 0; m < 4; ++m) _Pragma("unroll") for (int n = 0; n < 2; ++n) _Pragma("unroll") for (int k = 0; k < 2; ++k) \
;         acc[ai][bj][m][n] = __builtin_amdgcn_mfma_f32_16x16x32_bf16(Bt[n][k], At[m][k], acc[ai][bj][m][n], 0, 0, 0); __builtin_amdgcn_s_setprio(0); } while (0)
; #define PG8_WAIT_V(n) asm volatile("s_waitcnt vmcnt(" #n ")" ::: "memory")
; #define PG8_WAIT_L(n) asm volatile("s_waitcnt lgkmcnt(" #n ")" ::: "memory")
; #define PG8_BAR __builtin_amdgcn_s_barrier()
; #define PG8_SCHED __builtin_amdgcn_sched_barrier(0)
; template <class Epi, class Sched, bool ALIGN_EPI = false, bool SP2 = false>
; __device__ __forceinline__ void gemm_phase(PG8_LAS unsigned char* lds, const Gemm g, const Sched& S, const Epi& E, const int tid) {
;     ...
;             PG8_WAIT_V(8); PG8_WAIT_L(0); PG8_BAR; PG8_MMA(1, 0, At, B0); PG8_MMA(1, 1, At, B1); PG8_BAR; PG8_SCHED;
;             PG8_LDB(B0, 1, 0); PG8_LDB(B1, 1, 1); PG8_SCHED; PG8_LDA(At, 1, 0); PG8_STAGE(PG8_SA(0, 1), a2 + hstep, voffA);
;             PG8_WAIT_V(8); PG8_WAIT_L(0); PG8_BAR; PG8_MMA(0, 0, At, B0); PG8_MMA(0, 1, At, B1); PG8_BAR; PG8_SCHED;
	s_waitcnt lgkmcnt(0)
	v_mfma_f32_16x16x32_bf16 v[64:67], v[142:145], v[194:197], v[64:67]
	v_mfma_f32_16x16x32_bf16 v[56:59], v[170:173], v[194:197], v[56:59]
	v_mfma_f32_16x16x32_bf16 v[48:51], v[142:145], v[202:205], v[48:51]
	v_mfma_f32_16x16x32_bf16 v[40:43], v[170:173], v[202:205], v[40:43]
	v_mfma_f32_16x16x32_bf16 v[32:35], v[142:145], v[210:213], v[32:35]
	v_mfma_f32_16x16x32_bf16 v[24:27], v[170:173], v[210:213], v[24:27]
	v_mfma_f32_16x16x32_bf16 v[16:19], v[142:145], v[218:221], v[16:19]
	v_mfma_f32_16x16x32_bf16 v[8:11], v[170:173], v[218:221], v[8:11]
	v_mfma_f32_16x16x32_bf16 v[64:67], v[166:169], v[198:201], v[64:67]
	v_mfma_f32_16x16x32_bf16 v[56:59], v[174:177], v[198:201], v[56:59]
	v_mfma_f32_16x16x32_bf16 v[48:51], v[166:169], v[206:209], v[48:51]
	v_mfma_f32_16x16x32_bf16 v[40:43], v[174:177], v[206:209], v[40:43]
	v_mfma_f32_16x16x32_bf16 v[32:35], v[166:169], v[214:217], v[32:35]
	v_mfma_f32_16x16x32_bf16 v[24:27], v[174:177], v[214:217], v[24:27]
	v_mfma_f32_16x16x32_bf16 v[16:19], v[166:169], v[222:225], v[16:19]
	v_mfma_f32_16x16x32_bf16 v[8:11], v[174:177], v[222:225], v[8:11]
	v_mfma_f32_16x16x32_bf16 v[60:63], v[178:181], v[194:197], v[60:63]
	v_mfma_f32_16x16x32_bf16 v[52:55], v[186:189], v[194:197], v[52:55]
	v_mfma_f32_16x16x32_bf16 v[44:47], v[178:181], v[202:205], v[44:47]
	v_mfma_f32_16x16x32_bf16 v[36:39], v[186:189], v[202:205], v[36:39]
	v_mfma_f32_16x16x32_bf16 v[28:31], v[178:181], v[210:213], v[28:31]
	v_mfma_f32_16x16x32_bf16 v[20:23], v[186:189], v[210:213], v[20:23]
	v_mfma_f32_16x16x32_bf16 v[12:15], v[178:181], v[218:221], v[12:15]
	v_mfma_f32_16x16x32_bf16 v[4:7], v[186:189], v[218:221], v[4:7]
	v_mfma_f32_16x16x32_bf16 v[60:63], v[182:185], v[198:201], v[60:63]
	v_mfma_f32_16x16x32_bf16 v[52:55], v[190:193], v[198:201], v[52:55]
	v_mfma_f32_16x16x32_bf16 v[44:47], v[182:185], v[206:209], v[44:47]
	v_mfma_f32_16x16x32_bf16 v[36:39], v[190:193], v[206:209], v[36:39]
	v_mfma_f32_16x16x32_bf16 v[28:31], v[182:185], v[214:217], v[28:31]
	v_mfma_f32_16x16x32_bf16 v[20:23], v[190:193], v[214:217], v[20:23]
	v_mfma_f32_16x16x32_bf16 v[12:15], v[182:185], v[222:225], v[12:15]
	v_mfma_f32_16x16x32_bf16 v[4:7], v[190:193], v[222:225], v[4:7]
	s_barrier
	s_add_i32 s52, 0, 0x18000
	v_add_u32_e32 v148, s52, v146
	s_add_i32 s53, 0, 0x1c000
	ds_read_b128 v[142:145], v148
	ds_read_b128 v[166:169], v148 offset:1024
	ds_read_b128 v[170:173], v148 offset:2048
	ds_read_b128 v[174:177], v148 offset:3072
	v_add_u32_e32 v148, s53, v146
	ds_read_b128 v[178:181], v148
	ds_read_b128 v[182:185], v148 offset:1024
	ds_read_b128 v[186:189], v148 offset:2048
	ds_read_b128 v[190:193], v148 offset:3072
	s_add_u32 s22, s22, 0x40000
	s_addc_u32 s23, s23, 0
	s_mov_b32 m0, s40
	v_lshl_add_u64 v[244:245], s[22:23], 0, v[136:137]
	ds_read_b128 v[194:197], v153 offset:32768
	ds_read_b128 v[198:201], v153 offset:33792
	ds_read_b128 v[202:205], v153 offset:34816
	ds_read_b128 v[206:209], v153 offset:35840
	ds_read_b128 v[210:213], v153 offset:36864
	ds_read_b128 v[214:217], v153 offset:37888
	ds_read_b128 v[218:221], v153 offset:38912
	ds_read_b128 v[222:225], v153 offset:39936
	global_load_lds_dwordx4 v[244:245], off
	v_lshl_add_u64 v[244:245], s[22:23], 0, v[132:133]
	s_mov_b32 m0, s41
	s_nop 0
	global_load_lds_dwordx4 v[244:245], off
	s_waitcnt vmcnt(8)
	s_waitcnt lgkmcnt(0)
	s_barrier
	s_waitcnt lgkmcnt(0)
	v_mfma_f32_16x16x32_bf16 v[128:131], v[142:145], v[194:197], v[128:131]
	v_mfma_f32_16x16x32_bf16 v[120:123], v[170:173], v[194:197], v[120:123]
	v_mfma_f32_16x16x32_bf16 v[112:115], v[142:145], v[202:205], v[112:115]
	v_mfma_f32_16x16x32_bf16 v[104:107], v[170:173], v[202:205], v[104:107]
	v_mfma_f32_16x16x32_bf16 v[96:99], v[142:145], v[210:213], v[96:99]
	v_mfma_f32_16x16x32_bf16 v[88:91], v[170:173], v[210:213], v[88:91]
	v_mfma_f32_16x16x32_bf16 v[80:83], v[142:145], v[218:221], v[80:83]
	v_mfma_f32_16x16x32_bf16 v[72:75], v[170:173], v[218:221], v[72:75]
	v_mfma_f32_16x16x32_bf16 v[128:131], v[166:169], v[198:201], v[128:131]
	v_mfma_f32_16x16x32_bf16 v[120:123], v[174:177], v[198:201], v[120:123]
	v_mfma_f32_16x16x32_bf16 v[112:115], v[166:169], v[206:209], v[112:115]
	v_mfma_f32_16x16x32_bf16 v[104:107], v[174:177], v[206:209], v[104:107]
	v_mfma_f32_16x16x32_bf16 v[96:99], v[166:169], v[214:217], v[96:99]
	v_mfma_f32_16x16x32_bf16 v[88:91], v[174:177], v[214:217], v[88:91]
	v_mfma_f32_16x16x32_bf16 v[80:83], v[166:169], v[222:225], v[80:83]
	v_mfma_f32_16x16x32_bf16 v[72:75], v[174:177], v[222:225], v[72:75]
	v_mfma_f32_16x16x32_bf16 v[124:127], v[178:181], v[194:197], v[124:127]
	v_mfma_f32_16x16x32_bf16 v[116:119], v[186:189], v[194:197], v[116:119]
	v_mfma_f32_16x16x32_bf16 v[108:111], v[178:181], v[202:205], v[108:111]
	v_mfma_f32_16x16x32_bf16 v[100:103], v[186:189], v[202:205], v[100:103]
	v_mfma_f32_16x16x32_bf16 v[92:95], v[178:181], v[210:213], v[92:95]
	v_mfma_f32_16x16x32_bf16 v[84:87], v[186:189], v[210:213], v[84:87]
	v_mfma_f32_16x16x32_bf16 v[76:79], v[178:181], v[218:221], v[76:79]
	v_mfma_f32_16x16x32_bf16 v[68:71], v[186:189], v[218:221], v[68:71]
	v_mfma_f32_16x16x32_bf16 v[124:127], v[182:185], v[198:201], v[124:127]
	v_mfma_f32_16x16x32_bf16 v[116:119], v[190:193], v[198:201], v[116:119]
	v_mfma_f32_16x16x32_bf16 v[108:111], v[182:185], v[206:209], v[108:111]
	v_mfma_f32_16x16x32_bf16 v[100:103], v[190:193], v[206:209], v[100:103]
	v_mfma_f32_16x16x32_bf16 v[92:95], v[182:185], v[214:217], v[92:95]
	v_mfma_f32_16x16x32_bf16 v[84:87], v[190:193], v[214:217], v[84:87]
	v_mfma_f32_16x16x32_bf16 v[76:79], v[182:185], v[222:225], v[76:79]
	v_mfma_f32_16x16x32_bf16 v[68:71], v[190:193], v[222:225], v[68:71]
	s_barrier
; #define PG8_STAGE(bufoff, gbase, voff) do { _Pragma("unroll") for (int _i = 0; _i < 2; ++_i) \
;         __builtin_amdgcn_global_load_lds((const unsigned*)((const char*)(gbase) + (voff)[_i]), (PG8_LAS unsigned*)(lds + (bufoff) + ldsw + _i * 8192), 16, 0, 0); } while (0)
; #define PG8_LDA(dst, b, h) do { _Pragma("unroll") for (int m = 0; m < 4; ++m) _Pragma("unroll") for (int k = 0; k < 2; ++k) dst[m][k] = *(const PG8_LAS bf16x8*)(lds + PG8_SA(b, h) + aoff + m * 2048 + k * 1024); } while (0)
; #define PG8_MMA(ai, bj, At, Bt) do { __builtin_amdgcn_s_setprio(1); _Pragma("unroll") for (int m = 0; m < 4; ++m) _Pragma("unroll") for (int n = 0; n < 2; ++n) _Pragma("unroll") for (int k = 0; k < 2; ++k) \
;         acc[ai][bj][m][n] = __builtin_amdgcn_mfma_f32_16x16x32_bf16(Bt[n][k], At[m][k], acc[ai][bj][m][n], 0, 0, 0); __builtin_amdgcn_s_setprio(0); } while (0)
; #define PG8_WAIT_V(n) asm volatile("s_waitcnt vmcnt(" #n ")" ::: "memory")
; #define PG8_WAIT_L(n) asm volatile("s_waitcnt lgkmcnt(" #n ")" ::: "memory")
; #define PG8_BAR __builtin_amdgcn_s_barrier()
; #define PG8_SCHED __builtin_amdgcn_sched_barrier(0)
; template <class Epi, class Sched, bool ALIGN_EPI = false, bool SP2 = false>
; __device__ __forceinline__ void gemm_phase(PG8_LAS unsigned char* lds, const Gemm g, const Sched& S, const Epi& E, const int tid) {
;     ...
;             PG8_LDA(At, 1, 1); PG8_STAGE(PG8_SB(1, 0), b3, voffB); PG8_STAGE(PG8_SB(1, 1), b3 + hstep, voffB); PG8_STAGE(PG8_SA(1, 0), a3, voffA);
;             PG8_WAIT_V(8); PG8_WAIT_L(0); PG8_BAR; PG8_MMA(1, 0, At, B0); PG8_MMA(1, 1, At, B1); PG8_BAR; PG8_SCHED;
;     ...
;         if constexpr (ALIGN_EPI) { if (wr == 0) PG8_BAR; }
	s_add_i32 s22, s52, s37
	v_lshl_add_u64 v[226:227], v[226:227], 0, s[0:1]
	s_mov_b32 m0, s22
	ds_read_b128 v[194:197], v153 offset:49152
	ds_read_b128 v[198:201], v153 offset:50176
	ds_read_b128 v[202:205], v153 offset:51200
	ds_read_b128 v[206:209], v153 offset:52224
	ds_read_b128 v[210:213], v153 offset:53248
	ds_read_b128 v[214:217], v153 offset:54272
	ds_read_b128 v[218:221], v153 offset:55296
	ds_read_b128 v[222:225], v153 offset:56320
	global_load_lds_dwordx4 v[226:227], off
	s_add_i32 m0, s22, 0x2000
	s_add_u32 s20, s20, 0x40080
	v_lshl_add_u64 v[226:227], v[238:239], 0, s[0:1]
	s_addc_u32 s21, s21, 0
	s_add_i32 s22, s53, s37
	global_load_lds_dwordx4 v[226:227], off
	v_lshl_add_u64 v[226:227], s[20:21], 0, v[134:135]
	s_mov_b32 m0, s22
	s_nop 0
	global_load_lds_dwordx4 v[226:227], off
	v_lshl_add_u64 v[226:227], s[20:21], 0, v[0:1]
	s_add_i32 m0, s22, 0x2000
	s_nop 0
	global_load_lds_dwordx4 v[226:227], off
	v_lshl_add_u64 v[226:227], v[240:241], 0, s[0:1]
	s_mov_b32 m0, s42
	s_nop 0
	global_load_lds_dwordx4 v[226:227], off
	v_lshl_add_u64 v[226:227], v[242:243], 0, s[0:1]
	s_mov_b32 m0, s43
	s_nop 0
	global_load_lds_dwordx4 v[226:227], off
	s_waitcnt vmcnt(8)
	s_waitcnt lgkmcnt(0)
	s_barrier
	s_waitcnt lgkmcnt(0)
	v_mfma_f32_16x16x32_bf16 v[64:67], v[142:145], v[194:197], v[64:67]
	v_mfma_f32_16x16x32_bf16 v[56:59], v[170:173], v[194:197], v[56:59]
	v_mfma_f32_16x16x32_bf16 v[48:51], v[142:145], v[202:205], v[48:51]
	v_mfma_f32_16x16x32_bf16 v[40:43], v[170:173], v[202:205], v[40:43]
	v_mfma_f32_16x16x32_bf16 v[32:35], v[142:145], v[210:213], v[32:35]
	v_mfma_f32_16x16x32_bf16 v[24:27], v[170:173], v[210:213], v[24:27]
	v_mfma_f32_16x16x32_bf16 v[16:19], v[142:145], v[218:221], v[16:19]
	v_mfma_f32_16x16x32_bf16 v[8:11], v[170:173], v[218:221], v[8:11]
	v_mfma_f32_16x16x32_bf16 v[64:67], v[166:169], v[198:201], v[64:67]
	v_mfma_f32_16x16x32_bf16 v[56:59], v[174:177], v[198:201], v[56:59]
	v_mfma_f32_16x16x32_bf16 v[48:51], v[166:169], v[206:209], v[48:51]
	v_mfma_f32_16x16x32_bf16 v[40:43], v[174:177], v[206:209], v[40:43]
	v_mfma_f32_16x16x32_bf16 v[32:35], v[166:169], v[214:217], v[32:35]
	v_mfma_f32_16x16x32_bf16 v[24:27], v[174:177], v[214:217], v[24:27]
	v_mfma_f32_16x16x32_bf16 v[16:19], v[166:169], v[222:225], v[16:19]
	v_mfma_f32_16x16x32_bf16 v[8:11], v[174:177], v[222:225], v[8:11]
	v_mfma_f32_16x16x32_bf16 v[60:63], v[178:181], v[194:197], v[60:63]
	v_mfma_f32_16x16x32_bf16 v[52:55], v[186:189], v[194:197], v[52:55]
	v_mfma_f32_16x16x32_bf16 v[44:47], v[178:181], v[202:205], v[44:47]
	v_mfma_f32_16x16x32_bf16 v[36:39], v[186:189], v[202:205], v[36:39]
	v_mfma_f32_16x16x32_bf16 v[28:31], v[178:181], v[210:213], v[28:31]
	v_mfma_f32_16x16x32_bf16 v[20:23], v[186:189], v[210:213], v[20:23]
	v_mfma_f32_16x16x32_bf16 v[12:15], v[178:181], v[218:221], v[12:15]
	v_mfma_f32_16x16x32_bf16 v[4:7], v[186:189], v[218:221], v[4:7]
	v_mfma_f32_16x16x32_bf16 v[60:63], v[182:185], v[198:201], v[60:63]
	v_mfma_f32_16x16x32_bf16 v[52:55], v[190:193], v[198:201], v[52:55]
	v_mfma_f32_16x16x32_bf16 v[44:47], v[182:185], v[206:209], v[44:47]
	v_mfma_f32_16x16x32_bf16 v[36:39], v[190:193], v[206:209], v[36:39]
	v_mfma_f32_16x16x32_bf16 v[28:31], v[182:185], v[214:217], v[28:31]
	v_mfma_f32_16x16x32_bf16 v[20:23], v[190:193], v[214:217], v[20:23]
	v_mfma_f32_16x16x32_bf16 v[12:15], v[182:185], v[222:225], v[12:15]
	v_mfma_f32_16x16x32_bf16 v[4:7], v[190:193], v[222:225], v[4:7]
	s_barrier
	s_add_i32 s51, s51, 2
	s_add_u32 s18, s18, 0x100
	s_addc_u32 s19, s19, 0
	s_add_u32 s49, s49, 0x100
	s_addc_u32 s50, s50, 0
	s_cmp_gt_u32 s51, 13
	s_cbranch_scc0 .LBB0_522
	s_and_b64 vcc, exec, s[8:9]
	s_cbranch_vccz .LBB0_525
	s_barrier

; #define PG8_STAGE(bufoff, gbase, voff) do { _Pragma("unroll") for (int _i = 0; _i < 2; ++_i) \
;         __builtin_amdgcn_global_load_lds((const unsigned*)((const char*)(gbase) + (voff)[_i]), (PG8_LAS unsigned*)(lds + (bufoff) + ldsw + _i * 8192), 16, 0, 0); } while (0)
; #define PG8_LDA(dst, b, h) do { _Pragma("unroll") for (int m = 0; m < 4; ++m) _Pragma("unroll") for (int k = 0; k < 2; ++k) dst[m][k] = *(const PG8_LAS bf16x8*)(lds + PG8_SA(b, h) + aoff + m * 2048 + k * 1024); } while (0)
; #define PG8_LDB(dst, b, h) do { _Pragma("unroll") for (int n = 0; n < 2; ++n) _Pragma("unroll") for (int k = 0; k < 2; ++k) dst[n][k] = *(const PG8_LAS bf16x8*)(lds + PG8_SB(b, h) + boff + n * 2048 + k * 1024); } while (0)
; #define PG8_MMA(ai, bj, At, Bt) do { __builtin_amdgcn_s_setprio(1); _Pragma("unroll") for (int m = 0; m < 4; ++m) _Pragma("unroll") for (int n = 0; n < 2; ++n) _Pragma("unroll") for (int k = 0; k < 2; ++k) \
;         acc[ai][bj][m][n] = __builtin_amdgcn_mfma_f32_16x16x32_bf16(Bt[n][k], At[m][k], acc[ai][bj][m][n], 0, 0, 0); __builtin_amdgcn_s_setprio(0); } while (0)
; #define PG8_WAIT_V(n) asm volatile("s_waitcnt vmcnt(" #n ")" ::: "memory")
; #define PG8_WAIT_L(n) asm volatile("s_waitcnt lgkmcnt(" #n ")" ::: "memory")
; #define PG8_BAR __builtin_amdgcn_s_barrier()
; #define PG8_SCHED __builtin_amdgcn_sched_barrier(0)
; template <class Epi, class Sched, bool ALIGN_EPI = false, bool SP2 = false>
; __device__ __forceinline__ void gemm_phase(PG8_LAS unsigned char* lds, const Gemm g, const Sched& S, const Epi& E, const int tid) {
;     ...
;             const bool last = (t == nt - 2);
;             const char* a1 = cA + (size_t)(t + 1) * kstep;
;             const char* a2 = last ? nA : cA + (size_t)(t + 2) * kstep; const char* b2 = last ? nB : cB + (size_t)(t + 2) * kstep;
;             const char* a3 = a2 + kstep; const char* b3 = b2 + kstep;
;             if (last && has_next) S.a_ready(nxt);
;             if constexpr (SP2) {
;             PG8_LDB(B0, 0, 0); PG8_LDB(B1, 0, 1); PG8_SCHED; PG8_LDA(At, 0, 0); PG8_STAGE(PG8_SA(1, 1), a1 + hstep, voffA);
;             PG8_WAIT_V(8); PG8_WAIT_L(0); PG8_BAR; PG8_MMA(0, 0, At, B0); PG8_MMA(0, 1, At, B1); PG8_BAR; PG8_SCHED;
;             PG8_LDA(At, 0, 1); PG8_STAGE(PG8_SB(0, 0), b2, voffB); PG8_STAGE(PG8_SB(0, 1), b2 + hstep, voffB); PG8_STAGE(PG8_SA(0, 0), a2, voffA);
.LBB0_842:
	s_add_u32 s24, s22, 0xfffc0080
	s_addc_u32 s25, s23, -1
	s_add_i32 s50, 0, 0x10000
	s_cmp_eq_u32 s49, 12
	s_cselect_b32 s27, s13, s25
	s_cselect_b32 s26, s19, s24
	v_add_u32_e32 v148, s50, v146
	s_cselect_b32 s25, s11, s48
	s_cselect_b32 s24, s46, s47
	s_add_i32 s52, 0, 0x14000
	ds_read_b128 v[142:145], v148
	ds_read_b128 v[166:169], v148 offset:1024
	ds_read_b128 v[170:173], v148 offset:2048
	ds_read_b128 v[174:177], v148 offset:3072
	v_add_u32_e32 v148, s52, v146
	ds_read_b128 v[178:181], v148
	ds_read_b128 v[182:185], v148 offset:1024
	ds_read_b128 v[186:189], v148 offset:2048
	ds_read_b128 v[190:193], v148 offset:3072
	v_lshl_add_u64 v[226:227], s[22:23], 0, v[138:139]
	s_add_i32 m0, s21, 0xc000
	ds_read_b128 v[194:197], v153
	ds_read_b128 v[198:201], v153 offset:1024
	ds_read_b128 v[202:205], v153 offset:2048
	ds_read_b128 v[206:209], v153 offset:3072
	ds_read_b128 v[210:213], v153 offset:4096
	ds_read_b128 v[214:217], v153 offset:5120
	ds_read_b128 v[218:221], v153 offset:6144
	ds_read_b128 v[222:225], v153 offset:7168
	global_load_lds_dwordx4 v[226:227], off
	v_lshl_add_u64 v[226:227], s[22:23], 0, v[140:141]
	s_add_i32 m0, s21, 0xe000
	s_nop 0
	global_load_lds_dwordx4 v[226:227], off
	s_waitcnt vmcnt(8)
	s_waitcnt lgkmcnt(0)
	s_barrier
	s_waitcnt lgkmcnt(0)
	v_mfma_f32_16x16x32_bf16 v[128:131], v[142:145], v[194:197], v[128:131]
	v_mfma_f32_16x16x32_bf16 v[124:127], v[170:173], v[194:197], v[124:127]
	v_mfma_f32_16x16x32_bf16 v[112:115], v[142:145], v[202:205], v[112:115]
	v_mfma_f32_16x16x32_bf16 v[108:111], v[170:173], v[202:205], v[108:111]
	v_mfma_f32_16x16x32_bf16 v[96:99], v[142:145], v[210:213], v[96:99]
	v_mfma_f32_16x16x32_bf16 v[92:95], v[170:173], v[210:213], v[92:95]
	v_mfma_f32_16x16x32_bf16 v[80:83], v[142:145], v[218:221], v[80:83]
	v_mfma_f32_16x16x32_bf16 v[76:79], v[170:173], v[218:221], v[76:79]
	v_mfma_f32_16x16x32_bf16 v[128:131], v[166:169], v[198:201], v[128:131]
	v_mfma_f32_16x16x32_bf16 v[124:127], v[174:177], v[198:201], v[124:127]
	v_mfma_f32_16x16x32_bf16 v[112:115], v[166:169], v[206:209], v[112:115]
	v_mfma_f32_16x16x32_bf16 v[108:111], v[174:177], v[206:209], v[108:111]
	v_mfma_f32_16x16x32_bf16 v[96:99], v[166:169], v[214:217], v[96:99]
	v_mfma_f32_16x16x32_bf16 v[92:95], v[174:177], v[214:217], v[92:95]
	v_mfma_f32_16x16x32_bf16 v[80:83], v[166:169], v[222:225], v[80:83]
	v_mfma_f32_16x16x32_bf16 v[76:79], v[174:177], v[222:225], v[76:79]
	v_mfma_f32_16x16x32_bf16 v[120:123], v[178:181], v[194:197], v[120:123]
	v_mfma_f32_16x16x32_bf16 v[116:119], v[186:189], v[194:197], v[116:119]
	v_mfma_f32_16x16x32_bf16 v[104:107], v[178:181], v[202:205], v[104:107]
	v_mfma_f32_16x16x32_bf16 v[100:103], v[186:189], v[202:205], v[100:103]
	v_mfma_f32_16x16x32_bf16 v[88:91], v[178:181], v[210:213], v[88:91]
	v_mfma_f32_16x16x32_bf16 v[84:87], v[186:189], v[210:213], v[84:87]
	v_mfma_f32_16x16x32_bf16 v[72:75], v[178:181], v[218:221], v[72:75]
	v_mfma_f32_16x16x32_bf16 v[68:71], v[186:189], v[218:221], v[68:71]
	v_mfma_f32_16x16x32_bf16 v[120:123], v[182:185], v[198:201], v[120:123]
	v_mfma_f32_16x16x32_bf16 v[116:119], v[190:193], v[198:201], v[116:119]
	v_mfma_f32_16x16x32_bf16 v[104:107], v[182:185], v[206:209], v[104:107]
	v_mfma_f32_16x16x32_bf16 v[100:103], v[190:193], v[206:209], v[100:103]
	v_mfma_f32_16x16x32_bf16 v[88:91], v[182:185], v[214:217], v[88:91]
	v_mfma_f32_16x16x32_bf16 v[84:87], v[190:193], v[214:217], v[84:87]
	v_mfma_f32_16x16x32_bf16 v[72:75], v[182:185], v[222:225], v[72:75]
	v_mfma_f32_16x16x32_bf16 v[68:71], v[190:193], v[222:225], v[68:71]
	s_barrier
	s_add_i32 s50, s50, s37
	v_lshl_add_u64 v[226:227], s[24:25], 0, v[132:133]
	s_mov_b32 m0, s50
	ds_read_b128 v[194:197], v153 offset:16384
	ds_read_b128 v[198:201], v153 offset:17408
	ds_read_b128 v[202:205], v153 offset:18432
	ds_read_b128 v[206:209], v153 offset:19456
	ds_read_b128 v[210:213], v153 offset:20480
	ds_read_b128 v[214:217], v153 offset:21504
	ds_read_b128 v[218:221], v153 offset:22528
	ds_read_b128 v[222:225], v153 offset:23552
	global_load_lds_dwordx4 v[226:227], off
	s_add_i32 m0, s50, 0x2000
	s_add_u32 s50, s24, 0x40000
	v_lshl_add_u64 v[238:239], s[24:25], 0, v[136:137]
	s_addc_u32 s51, s25, 0
	s_add_i32 s52, s52, s37
	global_load_lds_dwordx4 v[238:239], off
	v_lshl_add_u64 v[240:241], s[50:51], 0, v[132:133]
	s_mov_b32 m0, s52
	v_lshl_add_u64 v[242:243], s[26:27], 0, v[134:135]
	global_load_lds_dwordx4 v[240:241], off
	v_lshl_add_u64 v[240:241], s[50:51], 0, v[136:137]
	s_add_i32 m0, s52, 0x2000
	s_nop 0
	global_load_lds_dwordx4 v[240:241], off
	v_lshl_add_u64 v[240:241], s[26:27], 0, v[0:1]
	s_mov_b32 m0, s21
	s_nop 0
	global_load_lds_dwordx4 v[240:241], off
	s_mov_b32 m0, s40
	s_nop 0
	global_load_lds_dwordx4 v[242:243], off
	s_waitcnt vmcnt(8)
	s_waitcnt lgkmcnt(0)
	s_barrier
; #define PG8_STAGE(bufoff, gbase, voff) do { _Pragma("unroll") for (int _i = 0; _i < 2; ++_i) \
;         __builtin_amdgcn_global_load_lds((const unsigned*)((const char*)(gbase) + (voff)[_i]), (PG8_LAS unsigned*)(lds + (bufoff) + ldsw + _i * 8192), 16, 0, 0); } while (0)
; #define PG8_LDA(dst, b, h) do { _Pragma("unroll") for (int m = 0; m < 4; ++m) _Pragma("unroll") for (int k = 0; k < 2; ++k) dst[m][k] = *(const PG8_LAS bf16x8*)(lds + PG8_SA(b, h) + aoff + m * 2048 + k * 1024); } while (0)
; #define PG8_LDB(dst, b, h) do { _Pragma("unroll") for (int n = 0; n < 2; ++n) _Pragma("unroll") for (int k = 0; k < 2; ++k) dst[n][k] = *(const PG8_LAS bf16x8*)(lds + PG8_SB(b, h) + boff + n * 2048 + k * 1024); } while (0)
; #define PG8_MMA(ai, bj, At, Bt) do { __builtin_amdgcn_s_setprio(1); _Pragma("unroll") for (int m = 0; m < 4; ++m) _Pragma("unroll") for (int n = 0; n < 2; ++n) _Pragma("unroll") for (int k = 0; k < 2; ++k) \
;         acc[ai][bj][m][n] = __builtin_amdgcn_mfma_f32_16x16x32_bf16(Bt[n][k], At[m][k], acc[ai][bj][m][n], 0, 0, 0); __builtin_amdgcn_s_setprio(0); } while (0)
; #define PG8_WAIT_V(n) asm volatile("s_waitcnt vmcnt(" #n ")" ::: "memory")
; #define PG8_WAIT_L(n) asm volatile("s_waitcnt lgkmcnt(" #n ")" ::: "memory")
; #define PG8_BAR __builtin_amdgcn_s_barrier()
; #define PG8_SCHED __builtin_amdgcn_sched_barrier(0)
; template <class Epi, class Sched, bool ALIGN_EPI = false, bool SP2 = false>
; __device__ __forceinline__ void gemm_phase(PG8_LAS unsigned char* lds, const Gemm g, const Sched& S, const Epi& E, const int tid) {
;     ...
;             PG8_WAIT_V(8); PG8_WAIT_L(0); PG8_BAR; PG8_MMA(1, 0, At, B0); PG8_MMA(1, 1, At, B1); PG8_BAR; PG8_SCHED;
;             PG8_LDB(B0, 1, 0); PG8_LDB(B1, 1, 1); PG8_SCHED; PG8_LDA(At, 1, 0); PG8_STAGE(PG8_SA(0, 1), a2 + hstep, voffA);
;             PG8_WAIT_V(8); PG8_WAIT_L(0); PG8_BAR; PG8_MMA(0, 0, At, B0); PG8_MMA(0, 1, At, B1); PG8_BAR; PG8_SCHED;
	s_waitcnt lgkmcnt(0)
	v_mfma_f32_16x16x32_bf16 v[64:67], v[142:145], v[194:197], v[64:67]
	v_mfma_f32_16x16x32_bf16 v[60:63], v[170:173], v[194:197], v[60:63]
	v_mfma_f32_16x16x32_bf16 v[48:51], v[142:145], v[202:205], v[48:51]
	v_mfma_f32_16x16x32_bf16 v[44:47], v[170:173], v[202:205], v[44:47]
	v_mfma_f32_16x16x32_bf16 v[32:35], v[142:145], v[210:213], v[32:35]
	v_mfma_f32_16x16x32_bf16 v[28:31], v[170:173], v[210:213], v[28:31]
	v_mfma_f32_16x16x32_bf16 v[16:19], v[142:145], v[218:221], v[16:19]
	v_mfma_f32_16x16x32_bf16 v[12:15], v[170:173], v[218:221], v[12:15]
	v_mfma_f32_16x16x32_bf16 v[64:67], v[166:169], v[198:201], v[64:67]
	v_mfma_f32_16x16x32_bf16 v[60:63], v[174:177], v[198:201], v[60:63]
	v_mfma_f32_16x16x32_bf16 v[48:51], v[166:169], v[206:209], v[48:51]
	v_mfma_f32_16x16x32_bf16 v[44:47], v[174:177], v[206:209], v[44:47]
	v_mfma_f32_16x16x32_bf16 v[32:35], v[166:169], v[214:217], v[32:35]
	v_mfma_f32_16x16x32_bf16 v[28:31], v[174:177], v[214:217], v[28:31]
	v_mfma_f32_16x16x32_bf16 v[16:19], v[166:169], v[222:225], v[16:19]
	v_mfma_f32_16x16x32_bf16 v[12:15], v[174:177], v[222:225], v[12:15]
	v_mfma_f32_16x16x32_bf16 v[56:59], v[178:181], v[194:197], v[56:59]
	v_mfma_f32_16x16x32_bf16 v[52:55], v[186:189], v[194:197], v[52:55]
	v_mfma_f32_16x16x32_bf16 v[40:43], v[178:181], v[202:205], v[40:43]
	v_mfma_f32_16x16x32_bf16 v[36:39], v[186:189], v[202:205], v[36:39]
	v_mfma_f32_16x16x32_bf16 v[24:27], v[178:181], v[210:213], v[24:27]
	v_mfma_f32_16x16x32_bf16 v[20:23], v[186:189], v[210:213], v[20:23]
	v_mfma_f32_16x16x32_bf16 v[8:11], v[178:181], v[218:221], v[8:11]
	v_mfma_f32_16x16x32_bf16 v[4:7], v[186:189], v[218:221], v[4:7]
	v_mfma_f32_16x16x32_bf16 v[56:59], v[182:185], v[198:201], v[56:59]
	v_mfma_f32_16x16x32_bf16 v[52:55], v[190:193], v[198:201], v[52:55]
	v_mfma_f32_16x16x32_bf16 v[40:43], v[182:185], v[206:209], v[40:43]
	v_mfma_f32_16x16x32_bf16 v[36:39], v[190:193], v[206:209], v[36:39]
	v_mfma_f32_16x16x32_bf16 v[24:27], v[182:185], v[214:217], v[24:27]
	v_mfma_f32_16x16x32_bf16 v[20:23], v[190:193], v[214:217], v[20:23]
	v_mfma_f32_16x16x32_bf16 v[8:11], v[182:185], v[222:225], v[8:11]
	v_mfma_f32_16x16x32_bf16 v[4:7], v[190:193], v[222:225], v[4:7]
	s_barrier
	s_add_i32 s50, 0, 0x18000
	v_add_u32_e32 v148, s50, v146
	s_add_i32 s51, 0, 0x1c000
	ds_read_b128 v[142:145], v148
	ds_read_b128 v[166:169], v148 offset:1024
	ds_read_b128 v[170:173], v148 offset:2048
	ds_read_b128 v[174:177], v148 offset:3072
	v_add_u32_e32 v148, s51, v146
	ds_read_b128 v[178:181], v148
	ds_read_b128 v[182:185], v148 offset:1024
	ds_read_b128 v[186:189], v148 offset:2048
	ds_read_b128 v[190:193], v148 offset:3072
	s_add_u32 s26, s26, 0x40000
	s_addc_u32 s27, s27, 0
	s_mov_b32 m0, s41
	v_lshl_add_u64 v[244:245], s[26:27], 0, v[0:1]
	ds_read_b128 v[194:197], v153 offset:32768
	ds_read_b128 v[198:201], v153 offset:33792
	ds_read_b128 v[202:205], v153 offset:34816
	ds_read_b128 v[206:209], v153 offset:35840
	ds_read_b128 v[210:213], v153 offset:36864
	ds_read_b128 v[214:217], v153 offset:37888
	ds_read_b128 v[218:221], v153 offset:38912
	ds_read_b128 v[222:225], v153 offset:39936
	global_load_lds_dwordx4 v[244:245], off
	v_lshl_add_u64 v[244:245], s[26:27], 0, v[134:135]
	s_mov_b32 m0, s42
	s_nop 0
	global_load_lds_dwordx4 v[244:245], off
	s_waitcnt vmcnt(8)
	s_waitcnt lgkmcnt(0)
	s_barrier
	s_waitcnt lgkmcnt(0)
	v_mfma_f32_16x16x32_bf16 v[128:131], v[142:145], v[194:197], v[128:131]
	v_mfma_f32_16x16x32_bf16 v[124:127], v[170:173], v[194:197], v[124:127]
	v_mfma_f32_16x16x32_bf16 v[112:115], v[142:145], v[202:205], v[112:115]
	v_mfma_f32_16x16x32_bf16 v[108:111], v[170:173], v[202:205], v[108:111]
	v_mfma_f32_16x16x32_bf16 v[96:99], v[142:145], v[210:213], v[96:99]
	v_mfma_f32_16x16x32_bf16 v[92:95], v[170:173], v[210:213], v[92:95]
	v_mfma_f32_16x16x32_bf16 v[80:83], v[142:145], v[218:221], v[80:83]
	v_mfma_f32_16x16x32_bf16 v[76:79], v[170:173], v[218:221], v[76:79]
	v_mfma_f32_16x16x32_bf16 v[128:131], v[166:169], v[198:201], v[128:131]
	v_mfma_f32_16x16x32_bf16 v[124:127], v[174:177], v[198:201], v[124:127]
	v_mfma_f32_16x16x32_bf16 v[112:115], v[166:169], v[206:209], v[112:115]
	v_mfma_f32_16x16x32_bf16 v[108:111], v[174:177], v[206:209], v[108:111]
	v_mfma_f32_16x16x32_bf16 v[96:99], v[166:169], v[214:217], v[96:99]
	v_mfma_f32_16x16x32_bf16 v[92:95], v[174:177], v[214:217], v[92:95]
	v_mfma_f32_16x16x32_bf16 v[80:83], v[166:169], v[222:225], v[80:83]
	v_mfma_f32_16x16x32_bf16 v[76:79], v[174:177], v[222:225], v[76:79]
	v_mfma_f32_16x16x32_bf16 v[120:123], v[178:181], v[194:197], v[120:123]
	v_mfma_f32_16x16x32_bf16 v[116:119], v[186:189], v[194:197], v[116:119]
	v_mfma_f32_16x16x32_bf16 v[104:107], v[178:181], v[202:205], v[104:107]
	v_mfma_f32_16x16x32_bf16 v[100:103], v[186:189], v[202:205], v[100:103]
	v_mfma_f32_16x16x32_bf16 v[88:91], v[178:181], v[210:213], v[88:91]
	v_mfma_f32_16x16x32_bf16 v[84:87], v[186:189], v[210:213], v[84:87]
	v_mfma_f32_16x16x32_bf16 v[72:75], v[178:181], v[218:221], v[72:75]
	v_mfma_f32_16x16x32_bf16 v[68:71], v[186:189], v[218:221], v[68:71]
	v_mfma_f32_16x16x32_bf16 v[120:123], v[182:185], v[198:201], v[120:123]
	v_mfma_f32_16x16x32_bf16 v[116:119], v[190:193], v[198:201], v[116:119]
	v_mfma_f32_16x16x32_bf16 v[104:107], v[182:185], v[206:209], v[104:107]
	v_mfma_f32_16x16x32_bf16 v[100:103], v[190:193], v[206:209], v[100:103]
	v_mfma_f32_16x16x32_bf16 v[88:91], v[182:185], v[214:217], v[88:91]
	v_mfma_f32_16x16x32_bf16 v[84:87], v[190:193], v[214:217], v[84:87]
	v_mfma_f32_16x16x32_bf16 v[72:75], v[182:185], v[222:225], v[72:75]
	v_mfma_f32_16x16x32_bf16 v[68:71], v[190:193], v[222:225], v[68:71]
	s_barrier
; #define PG8_STAGE(bufoff, gbase, voff) do { _Pragma("unroll") for (int _i = 0; _i < 2; ++_i) \
;         __builtin_amdgcn_global_load_lds((const unsigned*)((const char*)(gbase) + (voff)[_i]), (PG8_LAS unsigned*)(lds + (bufoff) + ldsw + _i * 8192), 16, 0, 0); } while (0)
; #define PG8_LDA(dst, b, h) do { _Pragma("unroll") for (int m = 0; m < 4; ++m) _Pragma("unroll") for (int k = 0; k < 2; ++k) dst[m][k] = *(const PG8_LAS bf16x8*)(lds + PG8_SA(b, h) + aoff + m * 2048 + k * 1024); } while (0)
; #define PG8_MMA(ai, bj, At, Bt) do { __builtin_amdgcn_s_setprio(1); _Pragma("unroll") for (int m = 0; m < 4; ++m) _Pragma("unroll") for (int n = 0; n < 2; ++n) _Pragma("unroll") for (int k = 0; k < 2; ++k) \
;         acc[ai][bj][m][n] = __builtin_amdgcn_mfma_f32_16x16x32_bf16(Bt[n][k], At[m][k], acc[ai][bj][m][n], 0, 0, 0); __builtin_amdgcn_s_setprio(0); } while (0)
; #define PG8_WAIT_V(n) asm volatile("s_waitcnt vmcnt(" #n ")" ::: "memory")
; #define PG8_WAIT_L(n) asm volatile("s_waitcnt lgkmcnt(" #n ")" ::: "memory")
; #define PG8_BAR __builtin_amdgcn_s_barrier()
; #define PG8_SCHED __builtin_amdgcn_sched_barrier(0)
; template <class Epi, class Sched, bool ALIGN_EPI = false, bool SP2 = false>
; __device__ __forceinline__ void gemm_phase(PG8_LAS unsigned char* lds, const Gemm g, const Sched& S, const Epi& E, const int tid) {
;     ...
;             PG8_LDA(At, 1, 1); PG8_STAGE(PG8_SB(1, 0), b3, voffB); PG8_STAGE(PG8_SB(1, 1), b3 + hstep, voffB); PG8_STAGE(PG8_SA(1, 0), a3, voffA);
;             PG8_WAIT_V(8); PG8_WAIT_L(0); PG8_BAR; PG8_MMA(1, 0, At, B0); PG8_MMA(1, 1, At, B1); PG8_BAR; PG8_SCHED;
;     ...
;         if constexpr (ALIGN_EPI) { if (wr == 0) PG8_BAR; }
	s_add_i32 s26, s50, s37
	v_lshl_add_u64 v[226:227], v[226:227], 0, s[0:1]
	s_mov_b32 m0, s26
	ds_read_b128 v[194:197], v153 offset:49152
	ds_read_b128 v[198:201], v153 offset:50176
	ds_read_b128 v[202:205], v153 offset:51200
	ds_read_b128 v[206:209], v153 offset:52224
	ds_read_b128 v[210:213], v153 offset:53248
	ds_read_b128 v[214:217], v153 offset:54272
	ds_read_b128 v[218:221], v153 offset:55296
	ds_read_b128 v[222:225], v153 offset:56320
	global_load_lds_dwordx4 v[226:227], off
	s_add_i32 m0, s26, 0x2000
	s_add_u32 s24, s24, 0x40080
	v_lshl_add_u64 v[226:227], v[238:239], 0, s[0:1]
	s_addc_u32 s25, s25, 0
	s_add_i32 s26, s51, s37
	global_load_lds_dwordx4 v[226:227], off
	v_lshl_add_u64 v[226:227], s[24:25], 0, v[132:133]
	s_mov_b32 m0, s26
	s_nop 0
	global_load_lds_dwordx4 v[226:227], off
	v_lshl_add_u64 v[226:227], s[24:25], 0, v[136:137]
	s_add_i32 m0, s26, 0x2000
	s_nop 0
	global_load_lds_dwordx4 v[226:227], off
	v_lshl_add_u64 v[226:227], v[240:241], 0, s[0:1]
	s_mov_b32 m0, s43
	s_nop 0
	global_load_lds_dwordx4 v[226:227], off
	v_lshl_add_u64 v[226:227], v[242:243], 0, s[0:1]
	s_mov_b32 m0, s44
	s_nop 0
	global_load_lds_dwordx4 v[226:227], off
	s_waitcnt vmcnt(8)
	s_waitcnt lgkmcnt(0)
	s_barrier
	s_waitcnt lgkmcnt(0)
	v_mfma_f32_16x16x32_bf16 v[64:67], v[142:145], v[194:197], v[64:67]
	v_mfma_f32_16x16x32_bf16 v[60:63], v[170:173], v[194:197], v[60:63]
	v_mfma_f32_16x16x32_bf16 v[48:51], v[142:145], v[202:205], v[48:51]
	v_mfma_f32_16x16x32_bf16 v[44:47], v[170:173], v[202:205], v[44:47]
	v_mfma_f32_16x16x32_bf16 v[32:35], v[142:145], v[210:213], v[32:35]
	v_mfma_f32_16x16x32_bf16 v[28:31], v[170:173], v[210:213], v[28:31]
	v_mfma_f32_16x16x32_bf16 v[16:19], v[142:145], v[218:221], v[16:19]
	v_mfma_f32_16x16x32_bf16 v[12:15], v[170:173], v[218:221], v[12:15]
	v_mfma_f32_16x16x32_bf16 v[64:67], v[166:169], v[198:201], v[64:67]
	v_mfma_f32_16x16x32_bf16 v[60:63], v[174:177], v[198:201], v[60:63]
	v_mfma_f32_16x16x32_bf16 v[48:51], v[166:169], v[206:209], v[48:51]
	v_mfma_f32_16x16x32_bf16 v[44:47], v[174:177], v[206:209], v[44:47]
	v_mfma_f32_16x16x32_bf16 v[32:35], v[166:169], v[214:217], v[32:35]
	v_mfma_f32_16x16x32_bf16 v[28:31], v[174:177], v[214:217], v[28:31]
	v_mfma_f32_16x16x32_bf16 v[16:19], v[166:169], v[222:225], v[16:19]
	v_mfma_f32_16x16x32_bf16 v[12:15], v[174:177], v[222:225], v[12:15]
	v_mfma_f32_16x16x32_bf16 v[56:59], v[178:181], v[194:197], v[56:59]
	v_mfma_f32_16x16x32_bf16 v[52:55], v[186:189], v[194:197], v[52:55]
	v_mfma_f32_16x16x32_bf16 v[40:43], v[178:181], v[202:205], v[40:43]
	v_mfma_f32_16x16x32_bf16 v[36:39], v[186:189], v[202:205], v[36:39]
	v_mfma_f32_16x16x32_bf16 v[24:27], v[178:181], v[210:213], v[24:27]
	v_mfma_f32_16x16x32_bf16 v[20:23], v[186:189], v[210:213], v[20:23]
	v_mfma_f32_16x16x32_bf16 v[8:11], v[178:181], v[218:221], v[8:11]
	v_mfma_f32_16x16x32_bf16 v[4:7], v[186:189], v[218:221], v[4:7]
	v_mfma_f32_16x16x32_bf16 v[56:59], v[182:185], v[198:201], v[56:59]
	v_mfma_f32_16x16x32_bf16 v[52:55], v[190:193], v[198:201], v[52:55]
	v_mfma_f32_16x16x32_bf16 v[40:43], v[182:185], v[206:209], v[40:43]
	v_mfma_f32_16x16x32_bf16 v[36:39], v[190:193], v[206:209], v[36:39]
	v_mfma_f32_16x16x32_bf16 v[24:27], v[182:185], v[214:217], v[24:27]
	v_mfma_f32_16x16x32_bf16 v[20:23], v[190:193], v[214:217], v[20:23]
	v_mfma_f32_16x16x32_bf16 v[8:11], v[182:185], v[222:225], v[8:11]
	v_mfma_f32_16x16x32_bf16 v[4:7], v[190:193], v[222:225], v[4:7]
	s_barrier
	s_add_i32 s49, s49, 2
	s_add_u32 s22, s22, 0x100
	s_addc_u32 s23, s23, 0
	s_add_u32 s47, s47, 0x100
	s_addc_u32 s48, s48, 0
	s_cmp_gt_u32 s49, 13
	s_cbranch_scc0 .LBB0_842
	s_and_b64 vcc, exec, s[8:9]
	s_cbranch_vccz .LBB0_845
	s_barrier
